# barrier release fan-out to per-XCC words (32 pollers per word) + sample down-proj sgemm keeps 3 K-slices in flight, on top of v2
# baseline (speedup 1.0000x reference)
.LBB0_969:
	s_or_b64 exec, exec, s[4:5]
	v_cvt_f32_u32_e32 v6, v3
	s_waitcnt vmcnt(0)
	v_readfirstlane_b32 s2, v5
	v_sub_u32_e32 v5, 0, v3
	v_rcp_iflag_f32_e32 v6, v6
	v_add_u32_e32 v4, s2, v4
	v_mul_f32_e32 v6, 0x4f7ffffe, v6
	v_cvt_u32_f32_e32 v6, v6
	v_mul_lo_u32 v5, v5, v6
	v_mul_hi_u32 v5, v6, v5
	v_add_u32_e32 v5, v6, v5
	v_mul_hi_u32 v5, v4, v5
	v_mul_lo_u32 v6, v5, v3
	v_sub_u32_e32 v6, v4, v6
	v_add_u32_e32 v7, 1, v5
	v_cmp_ge_u32_e32 vcc, v6, v3
	v_add_u32_e32 v4, 1, v4
	s_nop 0
	v_cndmask_b32_e32 v5, v5, v7, vcc
	v_sub_u32_e32 v7, v6, v3
	v_cndmask_b32_e32 v6, v6, v7, vcc
	v_add_u32_e32 v7, 1, v5
	v_cmp_ge_u32_e32 vcc, v6, v3
	s_nop 1
	v_cndmask_b32_e32 v5, v5, v7, vcc
	v_mul_lo_u32 v5, v3, v5
	v_add_u32_e32 v3, v5, v3
	v_cmp_eq_u32_e32 vcc, v4, v3
	s_and_b64 exec, exec, vcc
	s_cbranch_execz .LBB0_972
	s_mov_b64 s[2:3], exec
	v_mbcnt_lo_u32_b32 v3, s2, 0
	v_mbcnt_hi_u32_b32 v3, s3, v3
	v_cmp_eq_u32_e32 vcc, 0, v3
	s_and_b64 s[4:5], exec, vcc
	s_mov_b64 exec, s[4:5]
	s_cbranch_execz .LBB0_972
	s_bcnt1_i32_b64 s2, s[2:3]
	v_mov_b32_e32 v3, s2
	v_readlane_b32 s2, v250, 53
	v_readlane_b32 s3, v250, 54
	s_nop 4
	global_atomic_add v209, v3, s[2:3]
	s_sub_u32 s2, s2, 0x900
	s_subb_u32 s3, s3, 0
	s_nop 1
	global_atomic_add v209, v3, s[2:3] offset:-2048
	global_atomic_add v209, v3, s[2:3] offset:-1792
	global_atomic_add v209, v3, s[2:3] offset:-1536
	global_atomic_add v209, v3, s[2:3] offset:-1280
	global_atomic_add v209, v3, s[2:3] offset:-1024
	global_atomic_add v209, v3, s[2:3] offset:-768
	global_atomic_add v209, v3, s[2:3] offset:-512
	global_atomic_add v209, v3, s[2:3] offset:-256
	global_atomic_add v209, v3, s[2:3] offset:0
	global_atomic_add v209, v3, s[2:3] offset:256
	global_atomic_add v209, v3, s[2:3] offset:512
	global_atomic_add v209, v3, s[2:3] offset:768
	global_atomic_add v209, v3, s[2:3] offset:1024
	global_atomic_add v209, v3, s[2:3] offset:1280
	global_atomic_add v209, v3, s[2:3] offset:1536
	global_atomic_add v209, v3, s[2:3] offset:1792

.LBB0_993:
	s_ashr_i32 s44, s58, 31
	s_lshr_b32 s44, s44, 29
	s_add_i32 s44, s58, s44
	s_lshr_b32 s45, s44, 3
	s_and_b32 s44, s44, 0x3fffff8
	s_sub_i32 s44, s58, s44
	s_lshl_b32 s59, s44, 6
	v_or_b32_e32 v0, s59, v93
	v_ashrrev_i32_e32 v1, 31, v0
	v_lshlrev_b64 v[16:17], 13, v[0:1]
	v_lshl_add_u64 v[28:29], v[80:81], 0, v[16:17]
	s_mov_b32 s44, 0x10000
	s_add_i32 s45, s45, s57
	v_add_co_u32_e32 v4, vcc, s44, v28
	s_lshl_b32 s60, s45, 5
	s_nop 0
	v_addc_co_u32_e32 v5, vcc, 0, v29, vcc
	s_mov_b32 s45, 0x20000
	v_add_co_u32_e32 v8, vcc, s45, v28
	s_mov_b32 s45, 0x30000
	s_nop 0
	v_addc_co_u32_e32 v9, vcc, 0, v29, vcc
	v_add_co_u32_e32 v12, vcc, s45, v28
	s_mov_b32 s45, 0x40000
	s_nop 0
	v_addc_co_u32_e32 v13, vcc, 0, v29, vcc
	v_add_co_u32_e32 v20, vcc, s45, v28
	s_mov_b32 s45, 0x50000
	s_nop 0
	v_addc_co_u32_e32 v21, vcc, 0, v29, vcc
	v_add_co_u32_e32 v24, vcc, s45, v28
	s_mov_b32 s45, 0x60000
	s_nop 0
	v_addc_co_u32_e32 v25, vcc, 0, v29, vcc
	v_or_b32_e32 v0, s60, v93
	v_add_co_u32_e32 v30, vcc, s45, v28
	v_ashrrev_i32_e32 v1, 31, v0
	s_nop 0
	v_addc_co_u32_e32 v31, vcc, 0, v29, vcc
	v_lshlrev_b64 v[18:19], 13, v[0:1]
	v_add_co_u32_e32 v32, vcc, 0x70000, v28
	v_lshl_add_u64 v[36:37], v[82:83], 0, v[18:19]
	s_nop 0
	v_addc_co_u32_e32 v33, vcc, 0, v29, vcc
	v_add_co_u32_e32 v38, vcc, s44, v36
	s_waitcnt lgkmcnt(0)
	global_load_dwordx4 v[0:3], v[28:29], off
	s_nop 0
	global_load_dwordx4 v[4:7], v[4:5], off
	v_addc_co_u32_e32 v39, vcc, 0, v37, vcc
	global_load_dwordx4 v[8:11], v[8:9], off
	s_nop 0
	global_load_dwordx4 v[12:15], v[12:13], off
	s_nop 0
	global_load_dwordx4 v[20:23], v[20:21], off
	s_nop 0
	global_load_dwordx4 v[24:27], v[24:25], off
	s_nop 0
	global_load_dwordx4 v[28:31], v[30:31], off
	s_nop 0
	global_load_dwordx4 v[32:35], v[32:33], off
	s_nop 0
	global_load_dwordx4 v[40:43], v[36:37], off
	global_load_dwordx4 v[48:51], v[38:39], off
	v_add_co_u32_e32 v38, vcc, 0x20000, v36
	s_nop 1
	v_addc_co_u32_e32 v39, vcc, 0, v37, vcc
	v_add_co_u32_e32 v36, vcc, 0x30000, v36
	s_nop 1
	v_addc_co_u32_e32 v37, vcc, 0, v37, vcc
	global_load_dwordx4 v[64:67], v[38:39], off
	global_load_dwordx4 v[68:71], v[36:37], off
	v_lshl_add_u64 v[88:89], v[84:85], 0, v[16:17]
	v_mov_b32_e32 v16, 0
	v_lshl_add_u64 v[90:91], v[86:87], 0, v[18:19]
	s_mov_b64 s[44:45], 0
	v_mov_b32_e32 v17, v16
	v_mov_b32_e32 v18, v16
	v_mov_b32_e32 v19, v16
	v_mov_b32_e32 v36, v16
	v_mov_b32_e32 v37, v16
	v_mov_b32_e32 v38, v16
	v_mov_b32_e32 v39, v16
	v_mov_b32_e32 v44, v16
	v_mov_b32_e32 v45, v16
	v_mov_b32_e32 v46, v16
	v_mov_b32_e32 v47, v16
	v_mov_b32_e32 v52, v16
	v_mov_b32_e32 v53, v16
	v_mov_b32_e32 v54, v16
	v_mov_b32_e32 v55, v16
	v_mov_b32_e32 v56, v16
	v_mov_b32_e32 v57, v16
	v_mov_b32_e32 v58, v16
	v_mov_b32_e32 v59, v16
	v_mov_b32_e32 v60, v16
	v_mov_b32_e32 v61, v16
	v_mov_b32_e32 v62, v16
	v_mov_b32_e32 v63, v16
	v_mov_b32_e32 v72, v16
	v_mov_b32_e32 v73, v16
	v_mov_b32_e32 v74, v16
	v_mov_b32_e32 v75, v16
	v_mov_b32_e32 v76, v16
	v_mov_b32_e32 v77, v16
	v_mov_b32_e32 v78, v16
	v_mov_b32_e32 v79, v16
	s_mov_b32 s61, 0x2a00000
	s_mov_b32 s62, 0x10e00000
	s_mov_b32 s63, 0x10e10000
	s_mov_b32 s75, 0x10e20000
	s_mov_b32 s88, 0x10e30000
	s_mov_b32 s90, 0x10e40000
	s_mov_b32 s91, 0x10e50000
	s_mov_b32 s52, 0x10e60000
	s_mov_b32 s53, 0x10e70000
	s_mov_b32 s54, 0x2a10000
	s_mov_b32 s56, 0x2a20000
	s_mov_b32 s0, 0x2a30000
	v_lshl_add_u64 v[148:149], v[88:89], 0, s[44:45]
	v_add_co_u32_e32 v124, vcc, s62, v148
	v_lshl_add_u64 v[164:165], v[90:91], 0, s[44:45]
	s_nop 0
	v_addc_co_u32_e32 v125, vcc, 0, v149, vcc
	v_add_co_u32_e32 v128, vcc, s63, v148
	s_nop 1
	v_addc_co_u32_e32 v129, vcc, 0, v149, vcc
	v_add_co_u32_e32 v132, vcc, s75, v148
	global_load_dwordx4 v[124:127], v[124:125], off offset:128
	s_nop 0
	global_load_dwordx4 v[128:131], v[128:129], off offset:128
	v_addc_co_u32_e32 v133, vcc, 0, v149, vcc
	v_add_co_u32_e32 v136, vcc, s88, v148
	s_nop 1
	v_addc_co_u32_e32 v137, vcc, 0, v149, vcc
	v_add_co_u32_e32 v140, vcc, s90, v148
	global_load_dwordx4 v[132:135], v[132:133], off offset:128
	s_nop 0
	global_load_dwordx4 v[136:139], v[136:137], off offset:128
	v_addc_co_u32_e32 v141, vcc, 0, v149, vcc
	v_add_co_u32_e32 v144, vcc, s91, v148
	s_nop 1
	v_addc_co_u32_e32 v145, vcc, 0, v149, vcc
	v_add_co_u32_e32 v150, vcc, s52, v148
	global_load_dwordx4 v[140:143], v[140:141], off offset:128
	s_nop 0
	global_load_dwordx4 v[144:147], v[144:145], off offset:128
	v_addc_co_u32_e32 v151, vcc, 0, v149, vcc
	v_add_co_u32_e32 v152, vcc, s53, v148
	s_nop 1
	v_addc_co_u32_e32 v153, vcc, 0, v149, vcc
	v_add_co_u32_e32 v156, vcc, s61, v164
	global_load_dwordx4 v[148:151], v[150:151], off offset:128
	s_nop 0
	global_load_dwordx4 v[152:155], v[152:153], off offset:128
	v_addc_co_u32_e32 v157, vcc, 0, v165, vcc
	v_add_co_u32_e32 v160, vcc, s54, v164
	s_nop 1
	v_addc_co_u32_e32 v161, vcc, 0, v165, vcc
	v_add_co_u32_e32 v166, vcc, s56, v164
	global_load_dwordx4 v[156:159], v[156:157], off offset:128
	s_nop 0
	global_load_dwordx4 v[160:163], v[160:161], off offset:128
	v_addc_co_u32_e32 v167, vcc, 0, v165, vcc
	v_add_co_u32_e32 v168, vcc, s0, v164
	s_nop 1
	v_addc_co_u32_e32 v169, vcc, 0, v165, vcc
	global_load_dwordx4 v[164:167], v[166:167], off offset:128
	s_nop 0
	global_load_dwordx4 v[168:171], v[168:169], off offset:128
	v_lshl_add_u64 v[196:197], v[88:89], 0, s[44:45]
	v_add_co_u32_e32 v172, vcc, s62, v196
	v_lshl_add_u64 v[240:241], v[90:91], 0, s[44:45]
	s_nop 0
	v_addc_co_u32_e32 v173, vcc, 0, v197, vcc
	v_add_co_u32_e32 v176, vcc, s63, v196
	s_nop 1
	v_addc_co_u32_e32 v177, vcc, 0, v197, vcc
	v_add_co_u32_e32 v180, vcc, s75, v196
	global_load_dwordx4 v[172:175], v[172:173], off offset:256
	s_nop 0
	global_load_dwordx4 v[176:179], v[176:177], off offset:256
	v_addc_co_u32_e32 v181, vcc, 0, v197, vcc
	v_add_co_u32_e32 v184, vcc, s88, v196
	s_nop 1
	v_addc_co_u32_e32 v185, vcc, 0, v197, vcc
	v_add_co_u32_e32 v188, vcc, s90, v196
	global_load_dwordx4 v[180:183], v[180:181], off offset:256
	s_nop 0
	global_load_dwordx4 v[184:187], v[184:185], off offset:256
	v_addc_co_u32_e32 v189, vcc, 0, v197, vcc
	v_add_co_u32_e32 v192, vcc, s91, v196
	s_nop 1
	v_addc_co_u32_e32 v193, vcc, 0, v197, vcc
	v_add_co_u32_e32 v198, vcc, s52, v196
	global_load_dwordx4 v[188:191], v[188:189], off offset:256
	s_nop 0
	global_load_dwordx4 v[192:195], v[192:193], off offset:256
	v_addc_co_u32_e32 v199, vcc, 0, v197, vcc
	v_add_co_u32_e32 v200, vcc, s53, v196
	s_nop 1
	v_addc_co_u32_e32 v201, vcc, 0, v197, vcc
	v_add_co_u32_e32 v204, vcc, s61, v240
	global_load_dwordx4 v[196:199], v[198:199], off offset:256
	s_nop 0
	global_load_dwordx4 v[200:203], v[200:201], off offset:256
	v_addc_co_u32_e32 v205, vcc, 0, v241, vcc
	v_add_co_u32_e32 v216, vcc, s54, v240
	s_nop 1
	v_addc_co_u32_e32 v217, vcc, 0, v241, vcc
	v_add_co_u32_e32 v242, vcc, s56, v240
	global_load_dwordx4 v[204:207], v[204:205], off offset:256
	s_nop 0
	global_load_dwordx4 v[216:219], v[216:217], off offset:256
	v_addc_co_u32_e32 v243, vcc, 0, v241, vcc
	v_add_co_u32_e32 v244, vcc, s0, v240
	s_nop 1
	v_addc_co_u32_e32 v245, vcc, 0, v241, vcc
	global_load_dwordx4 v[240:243], v[242:243], off offset:256
	s_nop 0
	global_load_dwordx4 v[244:247], v[244:245], off offset:256
	s_barrier
.LBB0_994:
	s_waitcnt vmcnt(35)
	ds_write_b128 v99, v[0:3]
	s_waitcnt vmcnt(34)
	ds_write_b128 v99, v[4:7] offset:1024
	s_waitcnt vmcnt(33)
	ds_write_b128 v99, v[8:11] offset:2048
	s_waitcnt vmcnt(32)
	ds_write_b128 v99, v[12:15] offset:3072
	s_waitcnt vmcnt(31)
	ds_write_b128 v99, v[20:23] offset:4096
	s_waitcnt vmcnt(30)
	ds_write_b128 v99, v[24:27] offset:5120
	s_waitcnt vmcnt(29)
	ds_write_b128 v99, v[28:31] offset:6144
	s_waitcnt vmcnt(28)
	ds_write_b128 v99, v[32:35] offset:7168
	s_waitcnt vmcnt(27)
	ds_write_b128 v99, v[40:43] offset:8192
	s_waitcnt vmcnt(26)
	ds_write_b128 v99, v[48:51] offset:9216
	s_waitcnt vmcnt(25)
	ds_write_b128 v99, v[64:67] offset:10240
	s_waitcnt vmcnt(24)
	ds_write_b128 v99, v[68:71] offset:11264
	v_lshl_add_u64 v[28:29], v[88:89], 0, s[44:45]
	v_add_co_u32_e32 v0, vcc, s62, v28
	v_lshl_add_u64 v[64:65], v[90:91], 0, s[44:45]
	s_nop 0
	v_addc_co_u32_e32 v1, vcc, 0, v29, vcc
	v_add_co_u32_e32 v4, vcc, s63, v28
	s_nop 1
	v_addc_co_u32_e32 v5, vcc, 0, v29, vcc
	v_add_co_u32_e32 v8, vcc, s75, v28
	global_load_dwordx4 v[0:3], v[0:1], off offset:384
	s_nop 0
	global_load_dwordx4 v[4:7], v[4:5], off offset:384
	v_addc_co_u32_e32 v9, vcc, 0, v29, vcc
	v_add_co_u32_e32 v12, vcc, s88, v28
	s_nop 1
	v_addc_co_u32_e32 v13, vcc, 0, v29, vcc
	v_add_co_u32_e32 v20, vcc, s90, v28
	global_load_dwordx4 v[8:11], v[8:9], off offset:384
	s_nop 0
	global_load_dwordx4 v[12:15], v[12:13], off offset:384
	v_addc_co_u32_e32 v21, vcc, 0, v29, vcc
	v_add_co_u32_e32 v24, vcc, s91, v28
	s_nop 1
	v_addc_co_u32_e32 v25, vcc, 0, v29, vcc
	v_add_co_u32_e32 v30, vcc, s52, v28
	global_load_dwordx4 v[20:23], v[20:21], off offset:384
	s_nop 0
	global_load_dwordx4 v[24:27], v[24:25], off offset:384
	v_addc_co_u32_e32 v31, vcc, 0, v29, vcc
	v_add_co_u32_e32 v32, vcc, s53, v28
	s_nop 1
	v_addc_co_u32_e32 v33, vcc, 0, v29, vcc
	v_add_co_u32_e32 v40, vcc, s61, v64
	global_load_dwordx4 v[28:31], v[30:31], off offset:384
	s_nop 0
	global_load_dwordx4 v[32:35], v[32:33], off offset:384
	v_addc_co_u32_e32 v41, vcc, 0, v65, vcc
	v_add_co_u32_e32 v48, vcc, s54, v64
	s_nop 1
	v_addc_co_u32_e32 v49, vcc, 0, v65, vcc
	v_add_co_u32_e32 v66, vcc, s56, v64
	global_load_dwordx4 v[40:43], v[40:41], off offset:384
	s_nop 0
	global_load_dwordx4 v[48:51], v[48:49], off offset:384
	v_addc_co_u32_e32 v67, vcc, 0, v65, vcc
	v_add_co_u32_e32 v68, vcc, s0, v64
	s_nop 1
	v_addc_co_u32_e32 v69, vcc, 0, v65, vcc
	global_load_dwordx4 v[64:67], v[66:67], off offset:384
	s_nop 0
	global_load_dwordx4 v[68:71], v[68:69], off offset:384
	ds_read_b128 v[102:105], v100 offset:8192
	ds_read_b128 v[106:109], v100
	ds_read_b128 v[110:113], v100 offset:10240
	s_waitcnt lgkmcnt(1)
	v_mfma_f32_16x16x32_bf16 v[76:79], v[102:105], v[106:109], v[76:79]
	s_waitcnt lgkmcnt(0)
	v_mfma_f32_16x16x32_bf16 v[72:75], v[110:113], v[106:109], v[72:75]
	ds_read_b128 v[106:109], v100 offset:2048
	s_waitcnt lgkmcnt(0)
	v_mfma_f32_16x16x32_bf16 v[60:63], v[102:105], v[106:109], v[60:63]
	v_mfma_f32_16x16x32_bf16 v[56:59], v[110:113], v[106:109], v[56:59]
	ds_read_b128 v[106:109], v100 offset:4096
	s_waitcnt lgkmcnt(0)
	v_mfma_f32_16x16x32_bf16 v[52:55], v[102:105], v[106:109], v[52:55]
	v_mfma_f32_16x16x32_bf16 v[44:47], v[110:113], v[106:109], v[44:47]
	ds_read_b128 v[106:109], v100 offset:6144
	s_waitcnt lgkmcnt(0)
	v_mfma_f32_16x16x32_bf16 v[36:39], v[102:105], v[106:109], v[36:39]
	ds_read_b128 v[102:105], v101 offset:8192
	v_mfma_f32_16x16x32_bf16 v[16:19], v[110:113], v[106:109], v[16:19]
	ds_read_b128 v[110:113], v101 offset:10240
	ds_read_b128 v[106:109], v101
	s_waitcnt lgkmcnt(0)
	v_mfma_f32_16x16x32_bf16 v[76:79], v[102:105], v[106:109], v[76:79]
	v_mfma_f32_16x16x32_bf16 v[72:75], v[110:113], v[106:109], v[72:75]
	ds_read_b128 v[106:109], v101 offset:2048
	s_waitcnt lgkmcnt(0)
	v_mfma_f32_16x16x32_bf16 v[60:63], v[102:105], v[106:109], v[60:63]
	v_mfma_f32_16x16x32_bf16 v[56:59], v[110:113], v[106:109], v[56:59]
	ds_read_b128 v[106:109], v101 offset:4096
	s_waitcnt lgkmcnt(0)
	v_mfma_f32_16x16x32_bf16 v[52:55], v[102:105], v[106:109], v[52:55]
	v_mfma_f32_16x16x32_bf16 v[44:47], v[110:113], v[106:109], v[44:47]
	ds_read_b128 v[106:109], v101 offset:6144
	s_waitcnt lgkmcnt(0)
	v_mfma_f32_16x16x32_bf16 v[36:39], v[102:105], v[106:109], v[36:39]
	v_mfma_f32_16x16x32_bf16 v[16:19], v[110:113], v[106:109], v[16:19]
	s_waitcnt vmcnt(35)
	ds_write_b128 v99, v[124:127]
	s_waitcnt vmcnt(34)
	ds_write_b128 v99, v[128:131] offset:1024
	s_waitcnt vmcnt(33)
	ds_write_b128 v99, v[132:135] offset:2048
	s_waitcnt vmcnt(32)
	ds_write_b128 v99, v[136:139] offset:3072
	s_waitcnt vmcnt(31)
	ds_write_b128 v99, v[140:143] offset:4096
	s_waitcnt vmcnt(30)
	ds_write_b128 v99, v[144:147] offset:5120
	s_waitcnt vmcnt(29)
	ds_write_b128 v99, v[148:151] offset:6144
	s_waitcnt vmcnt(28)
	ds_write_b128 v99, v[152:155] offset:7168
	s_waitcnt vmcnt(27)
	ds_write_b128 v99, v[156:159] offset:8192
	s_waitcnt vmcnt(26)
	ds_write_b128 v99, v[160:163] offset:9216
	s_waitcnt vmcnt(25)
	ds_write_b128 v99, v[164:167] offset:10240
	s_waitcnt vmcnt(24)
	ds_write_b128 v99, v[168:171] offset:11264
	v_lshl_add_u64 v[148:149], v[88:89], 0, s[44:45]
	v_add_co_u32_e32 v124, vcc, s62, v148
	v_lshl_add_u64 v[164:165], v[90:91], 0, s[44:45]
	s_nop 0
	v_addc_co_u32_e32 v125, vcc, 0, v149, vcc
	v_add_co_u32_e32 v128, vcc, s63, v148
	s_nop 1
	v_addc_co_u32_e32 v129, vcc, 0, v149, vcc
	v_add_co_u32_e32 v132, vcc, s75, v148
	global_load_dwordx4 v[124:127], v[124:125], off offset:512
	s_nop 0
	global_load_dwordx4 v[128:131], v[128:129], off offset:512
	v_addc_co_u32_e32 v133, vcc, 0, v149, vcc
	v_add_co_u32_e32 v136, vcc, s88, v148
	s_nop 1
	v_addc_co_u32_e32 v137, vcc, 0, v149, vcc
	v_add_co_u32_e32 v140, vcc, s90, v148
	global_load_dwordx4 v[132:135], v[132:133], off offset:512
	s_nop 0
	global_load_dwordx4 v[136:139], v[136:137], off offset:512
	v_addc_co_u32_e32 v141, vcc, 0, v149, vcc
	v_add_co_u32_e32 v144, vcc, s91, v148
	s_nop 1
	v_addc_co_u32_e32 v145, vcc, 0, v149, vcc
	v_add_co_u32_e32 v150, vcc, s52, v148
	global_load_dwordx4 v[140:143], v[140:141], off offset:512
	s_nop 0
	global_load_dwordx4 v[144:147], v[144:145], off offset:512
	v_addc_co_u32_e32 v151, vcc, 0, v149, vcc
	v_add_co_u32_e32 v152, vcc, s53, v148
	s_nop 1
	v_addc_co_u32_e32 v153, vcc, 0, v149, vcc
	v_add_co_u32_e32 v156, vcc, s61, v164
	global_load_dwordx4 v[148:151], v[150:151], off offset:512
	s_nop 0
	global_load_dwordx4 v[152:155], v[152:153], off offset:512
	v_addc_co_u32_e32 v157, vcc, 0, v165, vcc
	v_add_co_u32_e32 v160, vcc, s54, v164
	s_nop 1
	v_addc_co_u32_e32 v161, vcc, 0, v165, vcc
	v_add_co_u32_e32 v166, vcc, s56, v164
	global_load_dwordx4 v[156:159], v[156:157], off offset:512
	s_nop 0
	global_load_dwordx4 v[160:163], v[160:161], off offset:512
	v_addc_co_u32_e32 v167, vcc, 0, v165, vcc
	v_add_co_u32_e32 v168, vcc, s0, v164
	s_nop 1
	v_addc_co_u32_e32 v169, vcc, 0, v165, vcc
	global_load_dwordx4 v[164:167], v[166:167], off offset:512
	s_nop 0
	global_load_dwordx4 v[168:171], v[168:169], off offset:512
	ds_read_b128 v[102:105], v100 offset:8192
	ds_read_b128 v[106:109], v100
	ds_read_b128 v[110:113], v100 offset:10240
	s_waitcnt lgkmcnt(1)
	v_mfma_f32_16x16x32_bf16 v[76:79], v[102:105], v[106:109], v[76:79]
	s_waitcnt lgkmcnt(0)
	v_mfma_f32_16x16x32_bf16 v[72:75], v[110:113], v[106:109], v[72:75]
	ds_read_b128 v[106:109], v100 offset:2048
	s_waitcnt lgkmcnt(0)
	v_mfma_f32_16x16x32_bf16 v[60:63], v[102:105], v[106:109], v[60:63]
	v_mfma_f32_16x16x32_bf16 v[56:59], v[110:113], v[106:109], v[56:59]
	ds_read_b128 v[106:109], v100 offset:4096
	s_waitcnt lgkmcnt(0)
	v_mfma_f32_16x16x32_bf16 v[52:55], v[102:105], v[106:109], v[52:55]
	v_mfma_f32_16x16x32_bf16 v[44:47], v[110:113], v[106:109], v[44:47]
	ds_read_b128 v[106:109], v100 offset:6144
	s_waitcnt lgkmcnt(0)
	v_mfma_f32_16x16x32_bf16 v[36:39], v[102:105], v[106:109], v[36:39]
	ds_read_b128 v[102:105], v101 offset:8192
	v_mfma_f32_16x16x32_bf16 v[16:19], v[110:113], v[106:109], v[16:19]
	ds_read_b128 v[110:113], v101 offset:10240
	ds_read_b128 v[106:109], v101
	s_waitcnt lgkmcnt(0)
	v_mfma_f32_16x16x32_bf16 v[76:79], v[102:105], v[106:109], v[76:79]
	v_mfma_f32_16x16x32_bf16 v[72:75], v[110:113], v[106:109], v[72:75]
	ds_read_b128 v[106:109], v101 offset:2048
	s_waitcnt lgkmcnt(0)
	v_mfma_f32_16x16x32_bf16 v[60:63], v[102:105], v[106:109], v[60:63]
	v_mfma_f32_16x16x32_bf16 v[56:59], v[110:113], v[106:109], v[56:59]
	ds_read_b128 v[106:109], v101 offset:4096
	s_waitcnt lgkmcnt(0)
	v_mfma_f32_16x16x32_bf16 v[52:55], v[102:105], v[106:109], v[52:55]
	v_mfma_f32_16x16x32_bf16 v[44:47], v[110:113], v[106:109], v[44:47]
	ds_read_b128 v[106:109], v101 offset:6144
	s_waitcnt lgkmcnt(0)
	v_mfma_f32_16x16x32_bf16 v[36:39], v[102:105], v[106:109], v[36:39]
	v_mfma_f32_16x16x32_bf16 v[16:19], v[110:113], v[106:109], v[16:19]
	s_waitcnt vmcnt(35)
	ds_write_b128 v99, v[172:175]
	s_waitcnt vmcnt(34)
	ds_write_b128 v99, v[176:179] offset:1024
	s_waitcnt vmcnt(33)
	ds_write_b128 v99, v[180:183] offset:2048
	s_waitcnt vmcnt(32)
	ds_write_b128 v99, v[184:187] offset:3072
	s_waitcnt vmcnt(31)
	ds_write_b128 v99, v[188:191] offset:4096
	s_waitcnt vmcnt(30)
	ds_write_b128 v99, v[192:195] offset:5120
	s_waitcnt vmcnt(29)
	ds_write_b128 v99, v[196:199] offset:6144
	s_waitcnt vmcnt(28)
	ds_write_b128 v99, v[200:203] offset:7168
	s_waitcnt vmcnt(27)
	ds_write_b128 v99, v[204:207] offset:8192
	s_waitcnt vmcnt(26)
	ds_write_b128 v99, v[216:219] offset:9216
	s_waitcnt vmcnt(25)
	ds_write_b128 v99, v[240:243] offset:10240
	s_waitcnt vmcnt(24)
	ds_write_b128 v99, v[244:247] offset:11264
	v_lshl_add_u64 v[196:197], v[88:89], 0, s[44:45]
	v_add_co_u32_e32 v172, vcc, s62, v196
	v_lshl_add_u64 v[240:241], v[90:91], 0, s[44:45]
	s_nop 0
	v_addc_co_u32_e32 v173, vcc, 0, v197, vcc
	v_add_co_u32_e32 v176, vcc, s63, v196
	s_nop 1
	v_addc_co_u32_e32 v177, vcc, 0, v197, vcc
	v_add_co_u32_e32 v180, vcc, s75, v196
	global_load_dwordx4 v[172:175], v[172:173], off offset:640
	s_nop 0
	global_load_dwordx4 v[176:179], v[176:177], off offset:640
	v_addc_co_u32_e32 v181, vcc, 0, v197, vcc
	v_add_co_u32_e32 v184, vcc, s88, v196
	s_nop 1
	v_addc_co_u32_e32 v185, vcc, 0, v197, vcc
	v_add_co_u32_e32 v188, vcc, s90, v196
	global_load_dwordx4 v[180:183], v[180:181], off offset:640
	s_nop 0
	global_load_dwordx4 v[184:187], v[184:185], off offset:640
	v_addc_co_u32_e32 v189, vcc, 0, v197, vcc
	v_add_co_u32_e32 v192, vcc, s91, v196
	s_nop 1
	v_addc_co_u32_e32 v193, vcc, 0, v197, vcc
	v_add_co_u32_e32 v198, vcc, s52, v196
	global_load_dwordx4 v[188:191], v[188:189], off offset:640
	s_nop 0
	global_load_dwordx4 v[192:195], v[192:193], off offset:640
	v_addc_co_u32_e32 v199, vcc, 0, v197, vcc
	v_add_co_u32_e32 v200, vcc, s53, v196
	s_nop 1
	v_addc_co_u32_e32 v201, vcc, 0, v197, vcc
	v_add_co_u32_e32 v204, vcc, s61, v240
	global_load_dwordx4 v[196:199], v[198:199], off offset:640
	s_nop 0
	global_load_dwordx4 v[200:203], v[200:201], off offset:640
	v_addc_co_u32_e32 v205, vcc, 0, v241, vcc
	v_add_co_u32_e32 v216, vcc, s54, v240
	s_nop 1
	v_addc_co_u32_e32 v217, vcc, 0, v241, vcc
	v_add_co_u32_e32 v242, vcc, s56, v240
	global_load_dwordx4 v[204:207], v[204:205], off offset:640
	s_nop 0
	global_load_dwordx4 v[216:219], v[216:217], off offset:640
	v_addc_co_u32_e32 v243, vcc, 0, v241, vcc
	v_add_co_u32_e32 v244, vcc, s0, v240
	s_nop 1
	v_addc_co_u32_e32 v245, vcc, 0, v241, vcc
	global_load_dwordx4 v[240:243], v[242:243], off offset:640
	s_nop 0
	global_load_dwordx4 v[244:247], v[244:245], off offset:640
	ds_read_b128 v[102:105], v100 offset:8192
	ds_read_b128 v[106:109], v100
	ds_read_b128 v[110:113], v100 offset:10240
	s_waitcnt lgkmcnt(1)
	v_mfma_f32_16x16x32_bf16 v[76:79], v[102:105], v[106:109], v[76:79]
	s_waitcnt lgkmcnt(0)
	v_mfma_f32_16x16x32_bf16 v[72:75], v[110:113], v[106:109], v[72:75]
	ds_read_b128 v[106:109], v100 offset:2048
	s_waitcnt lgkmcnt(0)
	v_mfma_f32_16x16x32_bf16 v[60:63], v[102:105], v[106:109], v[60:63]
	v_mfma_f32_16x16x32_bf16 v[56:59], v[110:113], v[106:109], v[56:59]
	ds_read_b128 v[106:109], v100 offset:4096
	s_waitcnt lgkmcnt(0)
	v_mfma_f32_16x16x32_bf16 v[52:55], v[102:105], v[106:109], v[52:55]
	v_mfma_f32_16x16x32_bf16 v[44:47], v[110:113], v[106:109], v[44:47]
	ds_read_b128 v[106:109], v100 offset:6144
	s_waitcnt lgkmcnt(0)
	v_mfma_f32_16x16x32_bf16 v[36:39], v[102:105], v[106:109], v[36:39]
	ds_read_b128 v[102:105], v101 offset:8192
	v_mfma_f32_16x16x32_bf16 v[16:19], v[110:113], v[106:109], v[16:19]
	ds_read_b128 v[110:113], v101 offset:10240
	ds_read_b128 v[106:109], v101
	s_waitcnt lgkmcnt(0)
	v_mfma_f32_16x16x32_bf16 v[76:79], v[102:105], v[106:109], v[76:79]
	v_mfma_f32_16x16x32_bf16 v[72:75], v[110:113], v[106:109], v[72:75]
	ds_read_b128 v[106:109], v101 offset:2048
	s_waitcnt lgkmcnt(0)
	v_mfma_f32_16x16x32_bf16 v[60:63], v[102:105], v[106:109], v[60:63]
	v_mfma_f32_16x16x32_bf16 v[56:59], v[110:113], v[106:109], v[56:59]
	ds_read_b128 v[106:109], v101 offset:4096
	s_waitcnt lgkmcnt(0)
	v_mfma_f32_16x16x32_bf16 v[52:55], v[102:105], v[106:109], v[52:55]
	v_mfma_f32_16x16x32_bf16 v[44:47], v[110:113], v[106:109], v[44:47]
	ds_read_b128 v[106:109], v101 offset:6144
	s_waitcnt lgkmcnt(0)
	v_mfma_f32_16x16x32_bf16 v[36:39], v[102:105], v[106:109], v[36:39]
	v_mfma_f32_16x16x32_bf16 v[16:19], v[110:113], v[106:109], v[16:19]
	s_waitcnt vmcnt(35)
	ds_write_b128 v99, v[0:3]
	s_waitcnt vmcnt(34)
	ds_write_b128 v99, v[4:7] offset:1024
	s_waitcnt vmcnt(33)
	ds_write_b128 v99, v[8:11] offset:2048
	s_waitcnt vmcnt(32)
	ds_write_b128 v99, v[12:15] offset:3072
	s_waitcnt vmcnt(31)
	ds_write_b128 v99, v[20:23] offset:4096
	s_waitcnt vmcnt(30)
	ds_write_b128 v99, v[24:27] offset:5120
	s_waitcnt vmcnt(29)
	ds_write_b128 v99, v[28:31] offset:6144
	s_waitcnt vmcnt(28)
	ds_write_b128 v99, v[32:35] offset:7168
	s_waitcnt vmcnt(27)
	ds_write_b128 v99, v[40:43] offset:8192
	s_waitcnt vmcnt(26)
	ds_write_b128 v99, v[48:51] offset:9216
	s_waitcnt vmcnt(25)
	ds_write_b128 v99, v[64:67] offset:10240
	s_waitcnt vmcnt(24)
	ds_write_b128 v99, v[68:71] offset:11264
	v_lshl_add_u64 v[28:29], v[88:89], 0, s[44:45]
	v_add_co_u32_e32 v0, vcc, s62, v28
	v_lshl_add_u64 v[64:65], v[90:91], 0, s[44:45]
	s_nop 0
	v_addc_co_u32_e32 v1, vcc, 0, v29, vcc
	v_add_co_u32_e32 v4, vcc, s63, v28
	s_nop 1
	v_addc_co_u32_e32 v5, vcc, 0, v29, vcc
	v_add_co_u32_e32 v8, vcc, s75, v28
	global_load_dwordx4 v[0:3], v[0:1], off offset:768
	s_nop 0
	global_load_dwordx4 v[4:7], v[4:5], off offset:768
	v_addc_co_u32_e32 v9, vcc, 0, v29, vcc
	v_add_co_u32_e32 v12, vcc, s88, v28
	s_nop 1
	v_addc_co_u32_e32 v13, vcc, 0, v29, vcc
	v_add_co_u32_e32 v20, vcc, s90, v28
	global_load_dwordx4 v[8:11], v[8:9], off offset:768
	s_nop 0
	global_load_dwordx4 v[12:15], v[12:13], off offset:768
	v_addc_co_u32_e32 v21, vcc, 0, v29, vcc
	v_add_co_u32_e32 v24, vcc, s91, v28
	s_nop 1
	v_addc_co_u32_e32 v25, vcc, 0, v29, vcc
	v_add_co_u32_e32 v30, vcc, s52, v28
	global_load_dwordx4 v[20:23], v[20:21], off offset:768
	s_nop 0
	global_load_dwordx4 v[24:27], v[24:25], off offset:768
	v_addc_co_u32_e32 v31, vcc, 0, v29, vcc
	v_add_co_u32_e32 v32, vcc, s53, v28
	s_nop 1
	v_addc_co_u32_e32 v33, vcc, 0, v29, vcc
	v_add_co_u32_e32 v40, vcc, s61, v64
	global_load_dwordx4 v[28:31], v[30:31], off offset:768
	s_nop 0
	global_load_dwordx4 v[32:35], v[32:33], off offset:768
	v_addc_co_u32_e32 v41, vcc, 0, v65, vcc
	v_add_co_u32_e32 v48, vcc, s54, v64
	s_nop 1
	v_addc_co_u32_e32 v49, vcc, 0, v65, vcc
	v_add_co_u32_e32 v66, vcc, s56, v64
	global_load_dwordx4 v[40:43], v[40:41], off offset:768
	s_nop 0
	global_load_dwordx4 v[48:51], v[48:49], off offset:768
	v_addc_co_u32_e32 v67, vcc, 0, v65, vcc
	v_add_co_u32_e32 v68, vcc, s0, v64
	s_nop 1
	v_addc_co_u32_e32 v69, vcc, 0, v65, vcc
	global_load_dwordx4 v[64:67], v[66:67], off offset:768
	s_nop 0
	global_load_dwordx4 v[68:71], v[68:69], off offset:768
	ds_read_b128 v[102:105], v100 offset:8192
	ds_read_b128 v[106:109], v100
	ds_read_b128 v[110:113], v100 offset:10240
	s_waitcnt lgkmcnt(1)
	v_mfma_f32_16x16x32_bf16 v[76:79], v[102:105], v[106:109], v[76:79]
	s_waitcnt lgkmcnt(0)
	v_mfma_f32_16x16x32_bf16 v[72:75], v[110:113], v[106:109], v[72:75]
	ds_read_b128 v[106:109], v100 offset:2048
	s_waitcnt lgkmcnt(0)
	v_mfma_f32_16x16x32_bf16 v[60:63], v[102:105], v[106:109], v[60:63]
	v_mfma_f32_16x16x32_bf16 v[56:59], v[110:113], v[106:109], v[56:59]
	ds_read_b128 v[106:109], v100 offset:4096
	s_waitcnt lgkmcnt(0)
	v_mfma_f32_16x16x32_bf16 v[52:55], v[102:105], v[106:109], v[52:55]
	v_mfma_f32_16x16x32_bf16 v[44:47], v[110:113], v[106:109], v[44:47]
	ds_read_b128 v[106:109], v100 offset:6144
	s_waitcnt lgkmcnt(0)
	v_mfma_f32_16x16x32_bf16 v[36:39], v[102:105], v[106:109], v[36:39]
	ds_read_b128 v[102:105], v101 offset:8192
	v_mfma_f32_16x16x32_bf16 v[16:19], v[110:113], v[106:109], v[16:19]
	ds_read_b128 v[110:113], v101 offset:10240
	ds_read_b128 v[106:109], v101
	s_waitcnt lgkmcnt(0)
	v_mfma_f32_16x16x32_bf16 v[76:79], v[102:105], v[106:109], v[76:79]
	v_mfma_f32_16x16x32_bf16 v[72:75], v[110:113], v[106:109], v[72:75]
	ds_read_b128 v[106:109], v101 offset:2048
	s_waitcnt lgkmcnt(0)
	v_mfma_f32_16x16x32_bf16 v[60:63], v[102:105], v[106:109], v[60:63]
	v_mfma_f32_16x16x32_bf16 v[56:59], v[110:113], v[106:109], v[56:59]
	ds_read_b128 v[106:109], v101 offset:4096
	s_waitcnt lgkmcnt(0)
	v_mfma_f32_16x16x32_bf16 v[52:55], v[102:105], v[106:109], v[52:55]
	v_mfma_f32_16x16x32_bf16 v[44:47], v[110:113], v[106:109], v[44:47]
	ds_read_b128 v[106:109], v101 offset:6144
	s_waitcnt lgkmcnt(0)
	v_mfma_f32_16x16x32_bf16 v[36:39], v[102:105], v[106:109], v[36:39]
	v_mfma_f32_16x16x32_bf16 v[16:19], v[110:113], v[106:109], v[16:19]
	s_waitcnt vmcnt(35)
	ds_write_b128 v99, v[124:127]
	s_waitcnt vmcnt(34)
	ds_write_b128 v99, v[128:131] offset:1024
	s_waitcnt vmcnt(33)
	ds_write_b128 v99, v[132:135] offset:2048
	s_waitcnt vmcnt(32)
	ds_write_b128 v99, v[136:139] offset:3072
	s_waitcnt vmcnt(31)
	ds_write_b128 v99, v[140:143] offset:4096
	s_waitcnt vmcnt(30)
	ds_write_b128 v99, v[144:147] offset:5120
	s_waitcnt vmcnt(29)
	ds_write_b128 v99, v[148:151] offset:6144
	s_waitcnt vmcnt(28)
	ds_write_b128 v99, v[152:155] offset:7168
	s_waitcnt vmcnt(27)
	ds_write_b128 v99, v[156:159] offset:8192
	s_waitcnt vmcnt(26)
	ds_write_b128 v99, v[160:163] offset:9216
	s_waitcnt vmcnt(25)
	ds_write_b128 v99, v[164:167] offset:10240
	s_waitcnt vmcnt(24)
	ds_write_b128 v99, v[168:171] offset:11264
	v_lshl_add_u64 v[148:149], v[88:89], 0, s[44:45]
	v_add_co_u32_e32 v124, vcc, s62, v148
	v_lshl_add_u64 v[164:165], v[90:91], 0, s[44:45]
	s_nop 0
	v_addc_co_u32_e32 v125, vcc, 0, v149, vcc
	v_add_co_u32_e32 v128, vcc, s63, v148
	s_nop 1
	v_addc_co_u32_e32 v129, vcc, 0, v149, vcc
	v_add_co_u32_e32 v132, vcc, s75, v148
	global_load_dwordx4 v[124:127], v[124:125], off offset:896
	s_nop 0
	global_load_dwordx4 v[128:131], v[128:129], off offset:896
	v_addc_co_u32_e32 v133, vcc, 0, v149, vcc
	v_add_co_u32_e32 v136, vcc, s88, v148
	s_nop 1
	v_addc_co_u32_e32 v137, vcc, 0, v149, vcc
	v_add_co_u32_e32 v140, vcc, s90, v148
	global_load_dwordx4 v[132:135], v[132:133], off offset:896
	s_nop 0
	global_load_dwordx4 v[136:139], v[136:137], off offset:896
	v_addc_co_u32_e32 v141, vcc, 0, v149, vcc
	v_add_co_u32_e32 v144, vcc, s91, v148
	s_nop 1
	v_addc_co_u32_e32 v145, vcc, 0, v149, vcc
	v_add_co_u32_e32 v150, vcc, s52, v148
	global_load_dwordx4 v[140:143], v[140:141], off offset:896
	s_nop 0
	global_load_dwordx4 v[144:147], v[144:145], off offset:896
	v_addc_co_u32_e32 v151, vcc, 0, v149, vcc
	v_add_co_u32_e32 v152, vcc, s53, v148
	s_nop 1
	v_addc_co_u32_e32 v153, vcc, 0, v149, vcc
	v_add_co_u32_e32 v156, vcc, s61, v164
	global_load_dwordx4 v[148:151], v[150:151], off offset:896
	s_nop 0
	global_load_dwordx4 v[152:155], v[152:153], off offset:896
	v_addc_co_u32_e32 v157, vcc, 0, v165, vcc
	v_add_co_u32_e32 v160, vcc, s54, v164
	s_nop 1
	v_addc_co_u32_e32 v161, vcc, 0, v165, vcc
	v_add_co_u32_e32 v166, vcc, s56, v164
	global_load_dwordx4 v[156:159], v[156:157], off offset:896
	s_nop 0
	global_load_dwordx4 v[160:163], v[160:161], off offset:896
	v_addc_co_u32_e32 v167, vcc, 0, v165, vcc
	v_add_co_u32_e32 v168, vcc, s0, v164
	s_nop 1
	v_addc_co_u32_e32 v169, vcc, 0, v165, vcc
	global_load_dwordx4 v[164:167], v[166:167], off offset:896
	s_nop 0
	global_load_dwordx4 v[168:171], v[168:169], off offset:896
	ds_read_b128 v[102:105], v100 offset:8192
	ds_read_b128 v[106:109], v100
	ds_read_b128 v[110:113], v100 offset:10240
	s_waitcnt lgkmcnt(1)
	v_mfma_f32_16x16x32_bf16 v[76:79], v[102:105], v[106:109], v[76:79]
	s_waitcnt lgkmcnt(0)
	v_mfma_f32_16x16x32_bf16 v[72:75], v[110:113], v[106:109], v[72:75]
	ds_read_b128 v[106:109], v100 offset:2048
	s_waitcnt lgkmcnt(0)
	v_mfma_f32_16x16x32_bf16 v[60:63], v[102:105], v[106:109], v[60:63]
	v_mfma_f32_16x16x32_bf16 v[56:59], v[110:113], v[106:109], v[56:59]
	ds_read_b128 v[106:109], v100 offset:4096
	s_waitcnt lgkmcnt(0)
	v_mfma_f32_16x16x32_bf16 v[52:55], v[102:105], v[106:109], v[52:55]
	v_mfma_f32_16x16x32_bf16 v[44:47], v[110:113], v[106:109], v[44:47]
	ds_read_b128 v[106:109], v100 offset:6144
	s_waitcnt lgkmcnt(0)
	v_mfma_f32_16x16x32_bf16 v[36:39], v[102:105], v[106:109], v[36:39]
	ds_read_b128 v[102:105], v101 offset:8192
	v_mfma_f32_16x16x32_bf16 v[16:19], v[110:113], v[106:109], v[16:19]
	ds_read_b128 v[110:113], v101 offset:10240
	ds_read_b128 v[106:109], v101
	s_waitcnt lgkmcnt(0)
	v_mfma_f32_16x16x32_bf16 v[76:79], v[102:105], v[106:109], v[76:79]
	v_mfma_f32_16x16x32_bf16 v[72:75], v[110:113], v[106:109], v[72:75]
	ds_read_b128 v[106:109], v101 offset:2048
	s_waitcnt lgkmcnt(0)
	v_mfma_f32_16x16x32_bf16 v[60:63], v[102:105], v[106:109], v[60:63]
	v_mfma_f32_16x16x32_bf16 v[56:59], v[110:113], v[106:109], v[56:59]
	ds_read_b128 v[106:109], v101 offset:4096
	s_waitcnt lgkmcnt(0)
	v_mfma_f32_16x16x32_bf16 v[52:55], v[102:105], v[106:109], v[52:55]
	v_mfma_f32_16x16x32_bf16 v[44:47], v[110:113], v[106:109], v[44:47]
	ds_read_b128 v[106:109], v101 offset:6144
	s_waitcnt lgkmcnt(0)
	v_mfma_f32_16x16x32_bf16 v[36:39], v[102:105], v[106:109], v[36:39]
	v_mfma_f32_16x16x32_bf16 v[16:19], v[110:113], v[106:109], v[16:19]
	s_waitcnt vmcnt(35)
	ds_write_b128 v99, v[172:175]
	s_waitcnt vmcnt(34)
	ds_write_b128 v99, v[176:179] offset:1024
	s_waitcnt vmcnt(33)
	ds_write_b128 v99, v[180:183] offset:2048
	s_waitcnt vmcnt(32)
	ds_write_b128 v99, v[184:187] offset:3072
	s_waitcnt vmcnt(31)
	ds_write_b128 v99, v[188:191] offset:4096
	s_waitcnt vmcnt(30)
	ds_write_b128 v99, v[192:195] offset:5120
	s_waitcnt vmcnt(29)
	ds_write_b128 v99, v[196:199] offset:6144
	s_waitcnt vmcnt(28)
	ds_write_b128 v99, v[200:203] offset:7168
	s_waitcnt vmcnt(27)
	ds_write_b128 v99, v[204:207] offset:8192
	s_waitcnt vmcnt(26)
	ds_write_b128 v99, v[216:219] offset:9216
	s_waitcnt vmcnt(25)
	ds_write_b128 v99, v[240:243] offset:10240
	s_waitcnt vmcnt(24)
	ds_write_b128 v99, v[244:247] offset:11264
	ds_read_b128 v[102:105], v100 offset:8192
	ds_read_b128 v[106:109], v100
	ds_read_b128 v[110:113], v100 offset:10240
	s_waitcnt lgkmcnt(1)
	v_mfma_f32_16x16x32_bf16 v[76:79], v[102:105], v[106:109], v[76:79]
	s_waitcnt lgkmcnt(0)
	v_mfma_f32_16x16x32_bf16 v[72:75], v[110:113], v[106:109], v[72:75]
	ds_read_b128 v[106:109], v100 offset:2048
	s_waitcnt lgkmcnt(0)
	v_mfma_f32_16x16x32_bf16 v[60:63], v[102:105], v[106:109], v[60:63]
	v_mfma_f32_16x16x32_bf16 v[56:59], v[110:113], v[106:109], v[56:59]
	ds_read_b128 v[106:109], v100 offset:4096
	s_waitcnt lgkmcnt(0)
	v_mfma_f32_16x16x32_bf16 v[52:55], v[102:105], v[106:109], v[52:55]
	v_mfma_f32_16x16x32_bf16 v[44:47], v[110:113], v[106:109], v[44:47]
	ds_read_b128 v[106:109], v100 offset:6144
	s_waitcnt lgkmcnt(0)
	v_mfma_f32_16x16x32_bf16 v[36:39], v[102:105], v[106:109], v[36:39]
	ds_read_b128 v[102:105], v101 offset:8192
	v_mfma_f32_16x16x32_bf16 v[16:19], v[110:113], v[106:109], v[16:19]
	ds_read_b128 v[110:113], v101 offset:10240
	ds_read_b128 v[106:109], v101
	s_waitcnt lgkmcnt(0)
	v_mfma_f32_16x16x32_bf16 v[76:79], v[102:105], v[106:109], v[76:79]
	v_mfma_f32_16x16x32_bf16 v[72:75], v[110:113], v[106:109], v[72:75]
	ds_read_b128 v[106:109], v101 offset:2048
	s_waitcnt lgkmcnt(0)
	v_mfma_f32_16x16x32_bf16 v[60:63], v[102:105], v[106:109], v[60:63]
	v_mfma_f32_16x16x32_bf16 v[56:59], v[110:113], v[106:109], v[56:59]
	ds_read_b128 v[106:109], v101 offset:4096
	s_waitcnt lgkmcnt(0)
	v_mfma_f32_16x16x32_bf16 v[52:55], v[102:105], v[106:109], v[52:55]
	v_mfma_f32_16x16x32_bf16 v[44:47], v[110:113], v[106:109], v[44:47]
	ds_read_b128 v[106:109], v101 offset:6144
	s_waitcnt lgkmcnt(0)
	v_mfma_f32_16x16x32_bf16 v[36:39], v[102:105], v[106:109], v[36:39]
	v_mfma_f32_16x16x32_bf16 v[16:19], v[110:113], v[106:109], v[16:19]
	s_waitcnt vmcnt(23)
	ds_write_b128 v99, v[0:3]
	s_waitcnt vmcnt(22)
	ds_write_b128 v99, v[4:7] offset:1024
	s_waitcnt vmcnt(21)
	ds_write_b128 v99, v[8:11] offset:2048
	s_waitcnt vmcnt(20)
	ds_write_b128 v99, v[12:15] offset:3072
	s_waitcnt vmcnt(19)
	ds_write_b128 v99, v[20:23] offset:4096
	s_waitcnt vmcnt(18)
	ds_write_b128 v99, v[24:27] offset:5120
	s_waitcnt vmcnt(17)
	ds_write_b128 v99, v[28:31] offset:6144
	s_waitcnt vmcnt(16)
	ds_write_b128 v99, v[32:35] offset:7168
	s_waitcnt vmcnt(15)
	ds_write_b128 v99, v[40:43] offset:8192
	s_waitcnt vmcnt(14)
	ds_write_b128 v99, v[48:51] offset:9216
	s_waitcnt vmcnt(13)
	ds_write_b128 v99, v[64:67] offset:10240
	s_waitcnt vmcnt(12)
	ds_write_b128 v99, v[68:71] offset:11264
	ds_read_b128 v[102:105], v100 offset:8192
	ds_read_b128 v[106:109], v100
	ds_read_b128 v[110:113], v100 offset:10240
	s_waitcnt lgkmcnt(1)
	v_mfma_f32_16x16x32_bf16 v[76:79], v[102:105], v[106:109], v[76:79]
	s_waitcnt lgkmcnt(0)
	v_mfma_f32_16x16x32_bf16 v[72:75], v[110:113], v[106:109], v[72:75]
	ds_read_b128 v[106:109], v100 offset:2048
	s_waitcnt lgkmcnt(0)
	v_mfma_f32_16x16x32_bf16 v[60:63], v[102:105], v[106:109], v[60:63]
	v_mfma_f32_16x16x32_bf16 v[56:59], v[110:113], v[106:109], v[56:59]
	ds_read_b128 v[106:109], v100 offset:4096
	s_waitcnt lgkmcnt(0)
	v_mfma_f32_16x16x32_bf16 v[52:55], v[102:105], v[106:109], v[52:55]
	v_mfma_f32_16x16x32_bf16 v[44:47], v[110:113], v[106:109], v[44:47]
	ds_read_b128 v[106:109], v100 offset:6144
	s_waitcnt lgkmcnt(0)
	v_mfma_f32_16x16x32_bf16 v[36:39], v[102:105], v[106:109], v[36:39]
	ds_read_b128 v[102:105], v101 offset:8192
	v_mfma_f32_16x16x32_bf16 v[16:19], v[110:113], v[106:109], v[16:19]
	ds_read_b128 v[110:113], v101 offset:10240
	ds_read_b128 v[106:109], v101
	s_waitcnt lgkmcnt(0)
	v_mfma_f32_16x16x32_bf16 v[76:79], v[102:105], v[106:109], v[76:79]
	v_mfma_f32_16x16x32_bf16 v[72:75], v[110:113], v[106:109], v[72:75]
	ds_read_b128 v[106:109], v101 offset:2048
	s_waitcnt lgkmcnt(0)
	v_mfma_f32_16x16x32_bf16 v[60:63], v[102:105], v[106:109], v[60:63]
	v_mfma_f32_16x16x32_bf16 v[56:59], v[110:113], v[106:109], v[56:59]
	ds_read_b128 v[106:109], v101 offset:4096
	s_waitcnt lgkmcnt(0)
	v_mfma_f32_16x16x32_bf16 v[52:55], v[102:105], v[106:109], v[52:55]
	v_mfma_f32_16x16x32_bf16 v[44:47], v[110:113], v[106:109], v[44:47]
	ds_read_b128 v[106:109], v101 offset:6144
	s_waitcnt lgkmcnt(0)
	v_mfma_f32_16x16x32_bf16 v[36:39], v[102:105], v[106:109], v[36:39]
	v_mfma_f32_16x16x32_bf16 v[16:19], v[110:113], v[106:109], v[16:19]
	s_waitcnt vmcnt(11)
	ds_write_b128 v99, v[124:127]
	s_waitcnt vmcnt(10)
	ds_write_b128 v99, v[128:131] offset:1024
	s_waitcnt vmcnt(9)
	ds_write_b128 v99, v[132:135] offset:2048
	s_waitcnt vmcnt(8)
	ds_write_b128 v99, v[136:139] offset:3072
	s_waitcnt vmcnt(7)
	ds_write_b128 v99, v[140:143] offset:4096
	s_waitcnt vmcnt(6)
	ds_write_b128 v99, v[144:147] offset:5120
	s_waitcnt vmcnt(5)
	ds_write_b128 v99, v[148:151] offset:6144
	s_waitcnt vmcnt(4)
	ds_write_b128 v99, v[152:155] offset:7168
	s_waitcnt vmcnt(3)
	ds_write_b128 v99, v[156:159] offset:8192
	s_waitcnt vmcnt(2)
	ds_write_b128 v99, v[160:163] offset:9216
	s_waitcnt vmcnt(1)
	ds_write_b128 v99, v[164:167] offset:10240
	s_waitcnt vmcnt(0)
	ds_write_b128 v99, v[168:171] offset:11264
	ds_read_b128 v[0:3], v100 offset:8192
	ds_read_b128 v[4:7], v100
	ds_read_b128 v[12:15], v100 offset:10240
	ds_read_b128 v[40:43], v100 offset:6144
	ds_read_b128 v[20:23], v100 offset:2048
	ds_read_b128 v[28:31], v100 offset:4096
	s_waitcnt lgkmcnt(4)
	v_mfma_f32_16x16x32_bf16 v[8:11], v[0:3], v[4:7], v[76:79]
	s_waitcnt lgkmcnt(3)
	v_mfma_f32_16x16x32_bf16 v[4:7], v[12:15], v[4:7], v[72:75]
	s_waitcnt lgkmcnt(1)
	v_mfma_f32_16x16x32_bf16 v[24:27], v[0:3], v[20:23], v[60:63]
	v_mfma_f32_16x16x32_bf16 v[20:23], v[12:15], v[20:23], v[56:59]
	s_waitcnt lgkmcnt(0)
	v_mfma_f32_16x16x32_bf16 v[32:35], v[0:3], v[28:31], v[52:55]
	v_mfma_f32_16x16x32_bf16 v[28:31], v[12:15], v[28:31], v[44:47]
	v_mfma_f32_16x16x32_bf16 v[0:3], v[0:3], v[40:43], v[36:39]
	s_nop 2
	ds_read_b128 v[36:39], v101 offset:8192
	v_mfma_f32_16x16x32_bf16 v[12:15], v[12:15], v[40:43], v[16:19]
	ds_read_b128 v[40:43], v101 offset:10240
	s_nop 1
	ds_read_b128 v[16:19], v101
	s_waitcnt lgkmcnt(0)
	v_mfma_f32_16x16x32_bf16 v[8:11], v[36:39], v[16:19], v[8:11]
	v_mfma_f32_16x16x32_bf16 v[4:7], v[40:43], v[16:19], v[4:7]
	ds_read_b128 v[16:19], v101 offset:2048
	s_waitcnt lgkmcnt(0)
	v_mfma_f32_16x16x32_bf16 v[24:27], v[36:39], v[16:19], v[24:27]
	v_mfma_f32_16x16x32_bf16 v[16:19], v[40:43], v[16:19], v[20:23]
	s_nop 2
	ds_read_b128 v[20:23], v101 offset:4096
	s_waitcnt lgkmcnt(0)
	v_mfma_f32_16x16x32_bf16 v[32:35], v[36:39], v[20:23], v[32:35]
	v_mfma_f32_16x16x32_bf16 v[20:23], v[40:43], v[20:23], v[28:31]
	s_nop 2
	ds_read_b128 v[28:31], v101 offset:6144
	s_waitcnt lgkmcnt(0)
	v_mfma_f32_16x16x32_bf16 v[0:3], v[36:39], v[28:31], v[0:3]
	v_mfma_f32_16x16x32_bf16 v[12:15], v[40:43], v[28:31], v[12:15]
	s_barrier
	ds_write_b128 v94, v[8:11]
	ds_write_b128 v94, v[4:7] offset:1024
	ds_write_b128 v94, v[24:27] offset:2048
	ds_write_b128 v94, v[16:19] offset:3072
	ds_write_b128 v94, v[32:35] offset:4096
	ds_write_b128 v94, v[20:23] offset:5120
	ds_write_b128 v94, v[0:3] offset:6144
	ds_write_b128 v94, v[12:15] offset:7168
	s_waitcnt lgkmcnt(0)
	s_barrier
	s_and_saveexec_b64 s[44:45], s[4:5]
	s_cbranch_execz .LBB0_992
	ds_read_b128 v[0:3], v95
	ds_read_b128 v[4:7], v95 offset:8192
	v_add_u32_e32 v10, s60, v98
	v_ashrrev_i32_e32 v11, 31, v10
	v_lshlrev_b64 v[12:13], 2, v[10:11]
	v_lshlrev_b64 v[18:19], 1, v[10:11]
	s_waitcnt lgkmcnt(0)
	v_pk_add_f32 v[6:7], v[2:3], v[6:7]
	v_pk_add_f32 v[4:5], v[0:1], v[4:5]
	ds_read_b128 v[0:3], v95 offset:16384
	s_waitcnt lgkmcnt(0)
	v_pk_add_f32 v[6:7], v[6:7], v[2:3]
	v_pk_add_f32 v[4:5], v[4:5], v[0:1]
	ds_read_b128 v[0:3], v95 offset:24576
	s_waitcnt lgkmcnt(0)
	v_pk_add_f32 v[6:7], v[6:7], v[2:3]
	v_pk_add_f32 v[4:5], v[4:5], v[0:1]
	ds_read_b128 v[0:3], v95 offset:32768
	s_waitcnt lgkmcnt(0)
	v_pk_add_f32 v[6:7], v[6:7], v[2:3]
	v_pk_add_f32 v[4:5], v[4:5], v[0:1]
	ds_read_b128 v[0:3], v95 offset:40960
	s_waitcnt lgkmcnt(0)
	v_pk_add_f32 v[6:7], v[6:7], v[2:3]
	v_pk_add_f32 v[4:5], v[4:5], v[0:1]
	ds_read_b128 v[0:3], v95 offset:49152
	s_waitcnt lgkmcnt(0)
	v_pk_add_f32 v[6:7], v[6:7], v[2:3]
	v_pk_add_f32 v[4:5], v[4:5], v[0:1]
	ds_read_b128 v[0:3], v95 offset:57344
	s_waitcnt lgkmcnt(0)
	v_pk_add_f32 v[8:9], v[4:5], v[0:1]
	v_add_u32_e32 v1, s59, v96
	v_or_b32_e32 v0, v1, v97
	v_add_u32_e32 v4, 0xffffc000, v0
	v_lshrrev_b32_e32 v4, 2, v4
	v_cmp_gt_i32_e32 vcc, s74, v0
	v_ashrrev_i32_e32 v1, 12, v1
	v_add_u32_e32 v4, 4, v4
	v_cndmask_b32_e32 v22, v4, v1, vcc
	v_ashrrev_i32_e32 v1, 31, v0
	v_mov_b64_e32 v[4:5], s[30:31]
	v_lshlrev_b64 v[14:15], 11, v[0:1]
	v_mad_i64_i32 v[4:5], s[60:61], v22, s33, v[4:5]
	v_lshl_add_u64 v[16:17], s[34:35], 0, v[14:15]
	v_lshl_add_u64 v[4:5], v[4:5], 0, v[12:13]
	v_lshl_add_u64 v[10:11], v[16:17], 0, v[18:19]
	v_pk_add_f32 v[2:3], v[6:7], v[2:3]
	global_load_dwordx4 v[4:7], v[4:5], off
	s_andn2_b64 vcc, exec, s[22:23]
	global_load_dwordx2 v[16:17], v[10:11], off
	s_waitcnt vmcnt(0)
	v_lshlrev_b32_e32 v20, 16, v16
	v_and_b32_e32 v21, 0xffff0000, v16
	v_lshlrev_b32_e32 v16, 16, v17
	v_and_b32_e32 v17, 0xffff0000, v17
	v_pk_fma_f32 v[2:3], v[2:3], v[6:7], v[16:17]
	v_pk_fma_f32 v[4:5], v[8:9], v[4:5], v[20:21]
	v_cvt_pk_bf16_f32 v7, v2, v3
	v_cvt_pk_bf16_f32 v6, v4, v5
	global_store_dwordx2 v[10:11], v[6:7], off
	v_mov_b64_e32 v[10:11], s[42:43]
	v_mad_i64_i32 v[10:11], s[60:61], v22, s33, v[10:11]
	v_lshl_add_u64 v[10:11], v[10:11], 0, v[12:13]
	v_lshl_add_u64 v[6:7], s[40:41], 0, v[12:13]
	global_load_dwordx4 v[10:13], v[10:11], off
	s_waitcnt vmcnt(0)
	v_pk_add_f32 v[12:13], v[12:13], 1.0 op_sel_hi:[1,0]
	global_load_dwordx4 v[6:9], v[6:7], off
	v_pk_add_f32 v[10:11], v[10:11], 1.0 op_sel_hi:[1,0]
	s_waitcnt vmcnt(0)
	v_pk_mul_f32 v[8:9], v[8:9], v[12:13]
	v_pk_mul_f32 v[6:7], v[6:7], v[10:11]
	v_pk_mul_f32 v[8:9], v[8:9], v[2:3]
	v_pk_mul_f32 v[6:7], v[6:7], v[4:5]
	s_nop 0
	v_cvt_pk_bf16_f32 v6, v6, v7
	v_cvt_pk_bf16_f32 v7, v8, v9
	v_lshl_add_u64 v[8:9], s[38:39], 0, v[14:15]
	v_lshl_add_u64 v[8:9], v[8:9], 0, v[18:19]
	global_store_dwordx2 v[8:9], v[6:7], off
	s_cbranch_vccnz .LBB0_992
	v_mul_f32_e32 v5, v5, v5
	v_mul_f32_e32 v3, v3, v3
	v_fmac_f32_e32 v5, v4, v4
	v_fmac_f32_e32 v3, v2, v2
	v_add_f32_e32 v2, v5, v3
	ds_bpermute_b32 v3, v233, v2
	s_waitcnt lgkmcnt(0)
	v_add_f32_e32 v2, v2, v3
	ds_bpermute_b32 v3, v234, v2
	s_and_b64 exec, exec, s[6:7]
	s_cbranch_execz .LBB0_992
	s_waitcnt lgkmcnt(0)
	v_add_f32_e32 v2, v2, v3
	v_lshl_add_u64 v[0:1], v[0:1], 2, s[28:29]
	global_atomic_add_f32 v[0:1], v2, off
	s_branch .LBB0_992

.LBB0_1005:
	s_ashr_i32 s36, s50, 31
	s_lshr_b32 s36, s36, 29
	s_add_i32 s36, s50, s36
	s_lshr_b32 s37, s36, 3
	s_and_b32 s36, s36, 0x3fffff8
	s_sub_i32 s36, s50, s36
	s_lshl_b32 s39, s36, 6
	v_or_b32_e32 v0, s39, v93
	s_waitcnt lgkmcnt(0)
	v_ashrrev_i32_e32 v1, 31, v0
	v_lshlrev_b64 v[16:17], 13, v[0:1]
	v_lshl_add_u64 v[28:29], v[80:81], 0, v[16:17]
	v_add_co_u32_e32 v4, vcc, s58, v28
	s_mov_b32 s36, 0x20000
	s_nop 0
	v_addc_co_u32_e32 v5, vcc, 0, v29, vcc
	v_add_co_u32_e32 v8, vcc, s36, v28
	s_mov_b32 s36, 0x30000
	s_nop 0
	v_addc_co_u32_e32 v9, vcc, 0, v29, vcc
	v_add_co_u32_e32 v12, vcc, s36, v28
	s_mov_b32 s36, 0x40000
	s_nop 0
	v_addc_co_u32_e32 v13, vcc, 0, v29, vcc
	v_add_co_u32_e32 v20, vcc, s36, v28
	s_mov_b32 s36, 0x50000
	s_nop 0
	v_addc_co_u32_e32 v21, vcc, 0, v29, vcc
	s_add_i32 s37, s37, s38
	v_add_co_u32_e32 v24, vcc, s36, v28
	s_lshl_b32 s40, s37, 5
	s_nop 0
	v_addc_co_u32_e32 v25, vcc, 0, v29, vcc
	s_mov_b32 s36, 0x60000
	v_or_b32_e32 v0, s40, v93
	v_add_co_u32_e32 v30, vcc, s36, v28
	v_ashrrev_i32_e32 v1, 31, v0
	s_nop 0
	v_addc_co_u32_e32 v31, vcc, 0, v29, vcc
	v_lshlrev_b64 v[18:19], 13, v[0:1]
	v_add_co_u32_e32 v32, vcc, 0x70000, v28
	v_lshl_add_u64 v[36:37], v[82:83], 0, v[18:19]
	s_nop 0
	v_addc_co_u32_e32 v33, vcc, 0, v29, vcc
	v_add_co_u32_e32 v38, vcc, s58, v36
	global_load_dwordx4 v[0:3], v[28:29], off
	s_nop 0
	global_load_dwordx4 v[4:7], v[4:5], off
	v_addc_co_u32_e32 v39, vcc, 0, v37, vcc
	global_load_dwordx4 v[8:11], v[8:9], off
	s_nop 0
	global_load_dwordx4 v[12:15], v[12:13], off
	s_nop 0
	global_load_dwordx4 v[20:23], v[20:21], off
	s_nop 0
	global_load_dwordx4 v[24:27], v[24:25], off
	s_nop 0
	global_load_dwordx4 v[28:31], v[30:31], off
	s_nop 0
	global_load_dwordx4 v[32:35], v[32:33], off
	s_nop 0
	global_load_dwordx4 v[40:43], v[36:37], off
	global_load_dwordx4 v[48:51], v[38:39], off
	v_add_co_u32_e32 v38, vcc, 0x20000, v36
	s_nop 1
	v_addc_co_u32_e32 v39, vcc, 0, v37, vcc
	v_add_co_u32_e32 v36, vcc, 0x30000, v36
	s_nop 1
	v_addc_co_u32_e32 v37, vcc, 0, v37, vcc
	global_load_dwordx4 v[64:67], v[38:39], off
	global_load_dwordx4 v[68:71], v[36:37], off
	v_lshl_add_u64 v[88:89], v[84:85], 0, v[16:17]
	v_mov_b32_e32 v16, 0
	v_lshl_add_u64 v[90:91], v[86:87], 0, v[18:19]
	s_mov_b64 s[36:37], 0
	v_mov_b32_e32 v17, v16
	v_mov_b32_e32 v18, v16
	v_mov_b32_e32 v19, v16
	v_mov_b32_e32 v36, v16
	v_mov_b32_e32 v37, v16
	v_mov_b32_e32 v38, v16
	v_mov_b32_e32 v39, v16
	v_mov_b32_e32 v44, v16
	v_mov_b32_e32 v45, v16
	v_mov_b32_e32 v46, v16
	v_mov_b32_e32 v47, v16
	v_mov_b32_e32 v52, v16
	v_mov_b32_e32 v53, v16
	v_mov_b32_e32 v54, v16
	v_mov_b32_e32 v55, v16
	v_mov_b32_e32 v56, v16
	v_mov_b32_e32 v57, v16
	v_mov_b32_e32 v58, v16
	v_mov_b32_e32 v59, v16
	v_mov_b32_e32 v60, v16
	v_mov_b32_e32 v61, v16
	v_mov_b32_e32 v62, v16
	v_mov_b32_e32 v63, v16
	v_mov_b32_e32 v72, v16
	v_mov_b32_e32 v73, v16
	v_mov_b32_e32 v74, v16
	v_mov_b32_e32 v75, v16
	v_mov_b32_e32 v76, v16
	v_mov_b32_e32 v77, v16
	v_mov_b32_e32 v78, v16
	v_mov_b32_e32 v79, v16
	s_mov_b32 s41, 0x10e50000
	s_mov_b32 s42, 0x10e60000
	s_mov_b32 s43, 0x10e70000
	s_mov_b32 s57, 0x2a10000
	s_mov_b32 s75, 0x2a20000
	s_mov_b32 s88, 0x2a30000
	v_lshl_add_u64 v[148:149], v[88:89], 0, s[36:37]
	v_add_co_u32_e32 v124, vcc, s45, v148
	v_lshl_add_u64 v[164:165], v[90:91], 0, s[36:37]
	s_nop 0
	v_addc_co_u32_e32 v125, vcc, 0, v149, vcc
	v_add_co_u32_e32 v128, vcc, s52, v148
	s_nop 1
	v_addc_co_u32_e32 v129, vcc, 0, v149, vcc
	v_add_co_u32_e32 v132, vcc, s53, v148
	global_load_dwordx4 v[124:127], v[124:125], off offset:128
	s_nop 0
	global_load_dwordx4 v[128:131], v[128:129], off offset:128
	v_addc_co_u32_e32 v133, vcc, 0, v149, vcc
	v_add_co_u32_e32 v136, vcc, s54, v148
	s_nop 1
	v_addc_co_u32_e32 v137, vcc, 0, v149, vcc
	v_add_co_u32_e32 v140, vcc, s56, v148
	global_load_dwordx4 v[132:135], v[132:133], off offset:128
	s_nop 0
	global_load_dwordx4 v[136:139], v[136:137], off offset:128
	v_addc_co_u32_e32 v141, vcc, 0, v149, vcc
	v_add_co_u32_e32 v144, vcc, s41, v148
	s_nop 1
	v_addc_co_u32_e32 v145, vcc, 0, v149, vcc
	v_add_co_u32_e32 v150, vcc, s42, v148
	global_load_dwordx4 v[140:143], v[140:141], off offset:128
	s_nop 0
	global_load_dwordx4 v[144:147], v[144:145], off offset:128
	v_addc_co_u32_e32 v151, vcc, 0, v149, vcc
	v_add_co_u32_e32 v152, vcc, s43, v148
	s_nop 1
	v_addc_co_u32_e32 v153, vcc, 0, v149, vcc
	v_add_co_u32_e32 v156, vcc, s44, v164
	global_load_dwordx4 v[148:151], v[150:151], off offset:128
	s_nop 0
	global_load_dwordx4 v[152:155], v[152:153], off offset:128
	v_addc_co_u32_e32 v157, vcc, 0, v165, vcc
	v_add_co_u32_e32 v160, vcc, s57, v164
	s_nop 1
	v_addc_co_u32_e32 v161, vcc, 0, v165, vcc
	v_add_co_u32_e32 v166, vcc, s75, v164
	global_load_dwordx4 v[156:159], v[156:157], off offset:128
	s_nop 0
	global_load_dwordx4 v[160:163], v[160:161], off offset:128
	v_addc_co_u32_e32 v167, vcc, 0, v165, vcc
	v_add_co_u32_e32 v168, vcc, s88, v164
	s_nop 1
	v_addc_co_u32_e32 v169, vcc, 0, v165, vcc
	global_load_dwordx4 v[164:167], v[166:167], off offset:128
	s_nop 0
	global_load_dwordx4 v[168:171], v[168:169], off offset:128
	v_lshl_add_u64 v[196:197], v[88:89], 0, s[36:37]
	v_add_co_u32_e32 v172, vcc, s45, v196
	v_lshl_add_u64 v[240:241], v[90:91], 0, s[36:37]
	s_nop 0
	v_addc_co_u32_e32 v173, vcc, 0, v197, vcc
	v_add_co_u32_e32 v176, vcc, s52, v196
	s_nop 1
	v_addc_co_u32_e32 v177, vcc, 0, v197, vcc
	v_add_co_u32_e32 v180, vcc, s53, v196
	global_load_dwordx4 v[172:175], v[172:173], off offset:256
	s_nop 0
	global_load_dwordx4 v[176:179], v[176:177], off offset:256
	v_addc_co_u32_e32 v181, vcc, 0, v197, vcc
	v_add_co_u32_e32 v184, vcc, s54, v196
	s_nop 1
	v_addc_co_u32_e32 v185, vcc, 0, v197, vcc
	v_add_co_u32_e32 v188, vcc, s56, v196
	global_load_dwordx4 v[180:183], v[180:181], off offset:256
	s_nop 0
	global_load_dwordx4 v[184:187], v[184:185], off offset:256
	v_addc_co_u32_e32 v189, vcc, 0, v197, vcc
	v_add_co_u32_e32 v192, vcc, s41, v196
	s_nop 1
	v_addc_co_u32_e32 v193, vcc, 0, v197, vcc
	v_add_co_u32_e32 v198, vcc, s42, v196
	global_load_dwordx4 v[188:191], v[188:189], off offset:256
	s_nop 0
	global_load_dwordx4 v[192:195], v[192:193], off offset:256
	v_addc_co_u32_e32 v199, vcc, 0, v197, vcc
	v_add_co_u32_e32 v200, vcc, s43, v196
	s_nop 1
	v_addc_co_u32_e32 v201, vcc, 0, v197, vcc
	v_add_co_u32_e32 v204, vcc, s44, v240
	global_load_dwordx4 v[196:199], v[198:199], off offset:256
	s_nop 0
	global_load_dwordx4 v[200:203], v[200:201], off offset:256
	v_addc_co_u32_e32 v205, vcc, 0, v241, vcc
	v_add_co_u32_e32 v216, vcc, s57, v240
	s_nop 1
	v_addc_co_u32_e32 v217, vcc, 0, v241, vcc
	v_add_co_u32_e32 v242, vcc, s75, v240
	global_load_dwordx4 v[204:207], v[204:205], off offset:256
	s_nop 0
	global_load_dwordx4 v[216:219], v[216:217], off offset:256
	v_addc_co_u32_e32 v243, vcc, 0, v241, vcc
	v_add_co_u32_e32 v244, vcc, s88, v240
	s_nop 1
	v_addc_co_u32_e32 v245, vcc, 0, v241, vcc
	global_load_dwordx4 v[240:243], v[242:243], off offset:256
	s_nop 0
	global_load_dwordx4 v[244:247], v[244:245], off offset:256
	s_barrier
.LBB0_1006:
	s_waitcnt vmcnt(35)
	ds_write_b128 v99, v[0:3]
	s_waitcnt vmcnt(34)
	ds_write_b128 v99, v[4:7] offset:1024
	s_waitcnt vmcnt(33)
	ds_write_b128 v99, v[8:11] offset:2048
	s_waitcnt vmcnt(32)
	ds_write_b128 v99, v[12:15] offset:3072
	s_waitcnt vmcnt(31)
	ds_write_b128 v99, v[20:23] offset:4096
	s_waitcnt vmcnt(30)
	ds_write_b128 v99, v[24:27] offset:5120
	s_waitcnt vmcnt(29)
	ds_write_b128 v99, v[28:31] offset:6144
	s_waitcnt vmcnt(28)
	ds_write_b128 v99, v[32:35] offset:7168
	s_waitcnt vmcnt(27)
	ds_write_b128 v99, v[40:43] offset:8192
	s_waitcnt vmcnt(26)
	ds_write_b128 v99, v[48:51] offset:9216
	s_waitcnt vmcnt(25)
	ds_write_b128 v99, v[64:67] offset:10240
	s_waitcnt vmcnt(24)
	ds_write_b128 v99, v[68:71] offset:11264
	v_lshl_add_u64 v[28:29], v[88:89], 0, s[36:37]
	v_add_co_u32_e32 v0, vcc, s45, v28
	v_lshl_add_u64 v[64:65], v[90:91], 0, s[36:37]
	s_nop 0
	v_addc_co_u32_e32 v1, vcc, 0, v29, vcc
	v_add_co_u32_e32 v4, vcc, s52, v28
	s_nop 1
	v_addc_co_u32_e32 v5, vcc, 0, v29, vcc
	v_add_co_u32_e32 v8, vcc, s53, v28
	global_load_dwordx4 v[0:3], v[0:1], off offset:384
	s_nop 0
	global_load_dwordx4 v[4:7], v[4:5], off offset:384
	v_addc_co_u32_e32 v9, vcc, 0, v29, vcc
	v_add_co_u32_e32 v12, vcc, s54, v28
	s_nop 1
	v_addc_co_u32_e32 v13, vcc, 0, v29, vcc
	v_add_co_u32_e32 v20, vcc, s56, v28
	global_load_dwordx4 v[8:11], v[8:9], off offset:384
	s_nop 0
	global_load_dwordx4 v[12:15], v[12:13], off offset:384
	v_addc_co_u32_e32 v21, vcc, 0, v29, vcc
	v_add_co_u32_e32 v24, vcc, s41, v28
	s_nop 1
	v_addc_co_u32_e32 v25, vcc, 0, v29, vcc
	v_add_co_u32_e32 v30, vcc, s42, v28
	global_load_dwordx4 v[20:23], v[20:21], off offset:384
	s_nop 0
	global_load_dwordx4 v[24:27], v[24:25], off offset:384
	v_addc_co_u32_e32 v31, vcc, 0, v29, vcc
	v_add_co_u32_e32 v32, vcc, s43, v28
	s_nop 1
	v_addc_co_u32_e32 v33, vcc, 0, v29, vcc
	v_add_co_u32_e32 v40, vcc, s44, v64
	global_load_dwordx4 v[28:31], v[30:31], off offset:384
	s_nop 0
	global_load_dwordx4 v[32:35], v[32:33], off offset:384
	v_addc_co_u32_e32 v41, vcc, 0, v65, vcc
	v_add_co_u32_e32 v48, vcc, s57, v64
	s_nop 1
	v_addc_co_u32_e32 v49, vcc, 0, v65, vcc
	v_add_co_u32_e32 v66, vcc, s75, v64
	global_load_dwordx4 v[40:43], v[40:41], off offset:384
	s_nop 0
	global_load_dwordx4 v[48:51], v[48:49], off offset:384
	v_addc_co_u32_e32 v67, vcc, 0, v65, vcc
	v_add_co_u32_e32 v68, vcc, s88, v64
	s_nop 1
	v_addc_co_u32_e32 v69, vcc, 0, v65, vcc
	global_load_dwordx4 v[64:67], v[66:67], off offset:384
	s_nop 0
	global_load_dwordx4 v[68:71], v[68:69], off offset:384
	ds_read_b128 v[102:105], v100 offset:8192
	ds_read_b128 v[106:109], v100
	ds_read_b128 v[110:113], v100 offset:10240
	s_waitcnt lgkmcnt(1)
	v_mfma_f32_16x16x32_bf16 v[76:79], v[102:105], v[106:109], v[76:79]
	s_waitcnt lgkmcnt(0)
	v_mfma_f32_16x16x32_bf16 v[72:75], v[110:113], v[106:109], v[72:75]
	ds_read_b128 v[106:109], v100 offset:2048
	s_waitcnt lgkmcnt(0)
	v_mfma_f32_16x16x32_bf16 v[60:63], v[102:105], v[106:109], v[60:63]
	v_mfma_f32_16x16x32_bf16 v[56:59], v[110:113], v[106:109], v[56:59]
	ds_read_b128 v[106:109], v100 offset:4096
	s_waitcnt lgkmcnt(0)
	v_mfma_f32_16x16x32_bf16 v[52:55], v[102:105], v[106:109], v[52:55]
	v_mfma_f32_16x16x32_bf16 v[44:47], v[110:113], v[106:109], v[44:47]
	ds_read_b128 v[106:109], v100 offset:6144
	s_waitcnt lgkmcnt(0)
	v_mfma_f32_16x16x32_bf16 v[36:39], v[102:105], v[106:109], v[36:39]
	ds_read_b128 v[102:105], v101 offset:8192
	v_mfma_f32_16x16x32_bf16 v[16:19], v[110:113], v[106:109], v[16:19]
	ds_read_b128 v[110:113], v101 offset:10240
	ds_read_b128 v[106:109], v101
	s_waitcnt lgkmcnt(0)
	v_mfma_f32_16x16x32_bf16 v[76:79], v[102:105], v[106:109], v[76:79]
	v_mfma_f32_16x16x32_bf16 v[72:75], v[110:113], v[106:109], v[72:75]
	ds_read_b128 v[106:109], v101 offset:2048
	s_waitcnt lgkmcnt(0)
	v_mfma_f32_16x16x32_bf16 v[60:63], v[102:105], v[106:109], v[60:63]
	v_mfma_f32_16x16x32_bf16 v[56:59], v[110:113], v[106:109], v[56:59]
	ds_read_b128 v[106:109], v101 offset:4096
	s_waitcnt lgkmcnt(0)
	v_mfma_f32_16x16x32_bf16 v[52:55], v[102:105], v[106:109], v[52:55]
	v_mfma_f32_16x16x32_bf16 v[44:47], v[110:113], v[106:109], v[44:47]
	ds_read_b128 v[106:109], v101 offset:6144
	s_waitcnt lgkmcnt(0)
	v_mfma_f32_16x16x32_bf16 v[36:39], v[102:105], v[106:109], v[36:39]
	v_mfma_f32_16x16x32_bf16 v[16:19], v[110:113], v[106:109], v[16:19]
	s_waitcnt vmcnt(35)
	ds_write_b128 v99, v[124:127]
	s_waitcnt vmcnt(34)
	ds_write_b128 v99, v[128:131] offset:1024
	s_waitcnt vmcnt(33)
	ds_write_b128 v99, v[132:135] offset:2048
	s_waitcnt vmcnt(32)
	ds_write_b128 v99, v[136:139] offset:3072
	s_waitcnt vmcnt(31)
	ds_write_b128 v99, v[140:143] offset:4096
	s_waitcnt vmcnt(30)
	ds_write_b128 v99, v[144:147] offset:5120
	s_waitcnt vmcnt(29)
	ds_write_b128 v99, v[148:151] offset:6144
	s_waitcnt vmcnt(28)
	ds_write_b128 v99, v[152:155] offset:7168
	s_waitcnt vmcnt(27)
	ds_write_b128 v99, v[156:159] offset:8192
	s_waitcnt vmcnt(26)
	ds_write_b128 v99, v[160:163] offset:9216
	s_waitcnt vmcnt(25)
	ds_write_b128 v99, v[164:167] offset:10240
	s_waitcnt vmcnt(24)
	ds_write_b128 v99, v[168:171] offset:11264
	v_lshl_add_u64 v[148:149], v[88:89], 0, s[36:37]
	v_add_co_u32_e32 v124, vcc, s45, v148
	v_lshl_add_u64 v[164:165], v[90:91], 0, s[36:37]
	s_nop 0
	v_addc_co_u32_e32 v125, vcc, 0, v149, vcc
	v_add_co_u32_e32 v128, vcc, s52, v148
	s_nop 1
	v_addc_co_u32_e32 v129, vcc, 0, v149, vcc
	v_add_co_u32_e32 v132, vcc, s53, v148
	global_load_dwordx4 v[124:127], v[124:125], off offset:512
	s_nop 0
	global_load_dwordx4 v[128:131], v[128:129], off offset:512
	v_addc_co_u32_e32 v133, vcc, 0, v149, vcc
	v_add_co_u32_e32 v136, vcc, s54, v148
	s_nop 1
	v_addc_co_u32_e32 v137, vcc, 0, v149, vcc
	v_add_co_u32_e32 v140, vcc, s56, v148
	global_load_dwordx4 v[132:135], v[132:133], off offset:512
	s_nop 0
	global_load_dwordx4 v[136:139], v[136:137], off offset:512
	v_addc_co_u32_e32 v141, vcc, 0, v149, vcc
	v_add_co_u32_e32 v144, vcc, s41, v148
	s_nop 1
	v_addc_co_u32_e32 v145, vcc, 0, v149, vcc
	v_add_co_u32_e32 v150, vcc, s42, v148
	global_load_dwordx4 v[140:143], v[140:141], off offset:512
	s_nop 0
	global_load_dwordx4 v[144:147], v[144:145], off offset:512
	v_addc_co_u32_e32 v151, vcc, 0, v149, vcc
	v_add_co_u32_e32 v152, vcc, s43, v148
	s_nop 1
	v_addc_co_u32_e32 v153, vcc, 0, v149, vcc
	v_add_co_u32_e32 v156, vcc, s44, v164
	global_load_dwordx4 v[148:151], v[150:151], off offset:512
	s_nop 0
	global_load_dwordx4 v[152:155], v[152:153], off offset:512
	v_addc_co_u32_e32 v157, vcc, 0, v165, vcc
	v_add_co_u32_e32 v160, vcc, s57, v164
	s_nop 1
	v_addc_co_u32_e32 v161, vcc, 0, v165, vcc
	v_add_co_u32_e32 v166, vcc, s75, v164
	global_load_dwordx4 v[156:159], v[156:157], off offset:512
	s_nop 0
	global_load_dwordx4 v[160:163], v[160:161], off offset:512
	v_addc_co_u32_e32 v167, vcc, 0, v165, vcc
	v_add_co_u32_e32 v168, vcc, s88, v164
	s_nop 1
	v_addc_co_u32_e32 v169, vcc, 0, v165, vcc
	global_load_dwordx4 v[164:167], v[166:167], off offset:512
	s_nop 0
	global_load_dwordx4 v[168:171], v[168:169], off offset:512
	ds_read_b128 v[102:105], v100 offset:8192
	ds_read_b128 v[106:109], v100
	ds_read_b128 v[110:113], v100 offset:10240
	s_waitcnt lgkmcnt(1)
	v_mfma_f32_16x16x32_bf16 v[76:79], v[102:105], v[106:109], v[76:79]
	s_waitcnt lgkmcnt(0)
	v_mfma_f32_16x16x32_bf16 v[72:75], v[110:113], v[106:109], v[72:75]
	ds_read_b128 v[106:109], v100 offset:2048
	s_waitcnt lgkmcnt(0)
	v_mfma_f32_16x16x32_bf16 v[60:63], v[102:105], v[106:109], v[60:63]
	v_mfma_f32_16x16x32_bf16 v[56:59], v[110:113], v[106:109], v[56:59]
	ds_read_b128 v[106:109], v100 offset:4096
	s_waitcnt lgkmcnt(0)
	v_mfma_f32_16x16x32_bf16 v[52:55], v[102:105], v[106:109], v[52:55]
	v_mfma_f32_16x16x32_bf16 v[44:47], v[110:113], v[106:109], v[44:47]
	ds_read_b128 v[106:109], v100 offset:6144
	s_waitcnt lgkmcnt(0)
	v_mfma_f32_16x16x32_bf16 v[36:39], v[102:105], v[106:109], v[36:39]
	ds_read_b128 v[102:105], v101 offset:8192
	v_mfma_f32_16x16x32_bf16 v[16:19], v[110:113], v[106:109], v[16:19]
	ds_read_b128 v[110:113], v101 offset:10240
	ds_read_b128 v[106:109], v101
	s_waitcnt lgkmcnt(0)
	v_mfma_f32_16x16x32_bf16 v[76:79], v[102:105], v[106:109], v[76:79]
	v_mfma_f32_16x16x32_bf16 v[72:75], v[110:113], v[106:109], v[72:75]
	ds_read_b128 v[106:109], v101 offset:2048
	s_waitcnt lgkmcnt(0)
	v_mfma_f32_16x16x32_bf16 v[60:63], v[102:105], v[106:109], v[60:63]
	v_mfma_f32_16x16x32_bf16 v[56:59], v[110:113], v[106:109], v[56:59]
	ds_read_b128 v[106:109], v101 offset:4096
	s_waitcnt lgkmcnt(0)
	v_mfma_f32_16x16x32_bf16 v[52:55], v[102:105], v[106:109], v[52:55]
	v_mfma_f32_16x16x32_bf16 v[44:47], v[110:113], v[106:109], v[44:47]
	ds_read_b128 v[106:109], v101 offset:6144
	s_waitcnt lgkmcnt(0)
	v_mfma_f32_16x16x32_bf16 v[36:39], v[102:105], v[106:109], v[36:39]
	v_mfma_f32_16x16x32_bf16 v[16:19], v[110:113], v[106:109], v[16:19]
	s_waitcnt vmcnt(35)
	ds_write_b128 v99, v[172:175]
	s_waitcnt vmcnt(34)
	ds_write_b128 v99, v[176:179] offset:1024
	s_waitcnt vmcnt(33)
	ds_write_b128 v99, v[180:183] offset:2048
	s_waitcnt vmcnt(32)
	ds_write_b128 v99, v[184:187] offset:3072
	s_waitcnt vmcnt(31)
	ds_write_b128 v99, v[188:191] offset:4096
	s_waitcnt vmcnt(30)
	ds_write_b128 v99, v[192:195] offset:5120
	s_waitcnt vmcnt(29)
	ds_write_b128 v99, v[196:199] offset:6144
	s_waitcnt vmcnt(28)
	ds_write_b128 v99, v[200:203] offset:7168
	s_waitcnt vmcnt(27)
	ds_write_b128 v99, v[204:207] offset:8192
	s_waitcnt vmcnt(26)
	ds_write_b128 v99, v[216:219] offset:9216
	s_waitcnt vmcnt(25)
	ds_write_b128 v99, v[240:243] offset:10240
	s_waitcnt vmcnt(24)
	ds_write_b128 v99, v[244:247] offset:11264
	v_lshl_add_u64 v[196:197], v[88:89], 0, s[36:37]
	v_add_co_u32_e32 v172, vcc, s45, v196
	v_lshl_add_u64 v[240:241], v[90:91], 0, s[36:37]
	s_nop 0
	v_addc_co_u32_e32 v173, vcc, 0, v197, vcc
	v_add_co_u32_e32 v176, vcc, s52, v196
	s_nop 1
	v_addc_co_u32_e32 v177, vcc, 0, v197, vcc
	v_add_co_u32_e32 v180, vcc, s53, v196
	global_load_dwordx4 v[172:175], v[172:173], off offset:640
	s_nop 0
	global_load_dwordx4 v[176:179], v[176:177], off offset:640
	v_addc_co_u32_e32 v181, vcc, 0, v197, vcc
	v_add_co_u32_e32 v184, vcc, s54, v196
	s_nop 1
	v_addc_co_u32_e32 v185, vcc, 0, v197, vcc
	v_add_co_u32_e32 v188, vcc, s56, v196
	global_load_dwordx4 v[180:183], v[180:181], off offset:640
	s_nop 0
	global_load_dwordx4 v[184:187], v[184:185], off offset:640
	v_addc_co_u32_e32 v189, vcc, 0, v197, vcc
	v_add_co_u32_e32 v192, vcc, s41, v196
	s_nop 1
	v_addc_co_u32_e32 v193, vcc, 0, v197, vcc
	v_add_co_u32_e32 v198, vcc, s42, v196
	global_load_dwordx4 v[188:191], v[188:189], off offset:640
	s_nop 0
	global_load_dwordx4 v[192:195], v[192:193], off offset:640
	v_addc_co_u32_e32 v199, vcc, 0, v197, vcc
	v_add_co_u32_e32 v200, vcc, s43, v196
	s_nop 1
	v_addc_co_u32_e32 v201, vcc, 0, v197, vcc
	v_add_co_u32_e32 v204, vcc, s44, v240
	global_load_dwordx4 v[196:199], v[198:199], off offset:640
	s_nop 0
	global_load_dwordx4 v[200:203], v[200:201], off offset:640
	v_addc_co_u32_e32 v205, vcc, 0, v241, vcc
	v_add_co_u32_e32 v216, vcc, s57, v240
	s_nop 1
	v_addc_co_u32_e32 v217, vcc, 0, v241, vcc
	v_add_co_u32_e32 v242, vcc, s75, v240
	global_load_dwordx4 v[204:207], v[204:205], off offset:640
	s_nop 0
	global_load_dwordx4 v[216:219], v[216:217], off offset:640
	v_addc_co_u32_e32 v243, vcc, 0, v241, vcc
	v_add_co_u32_e32 v244, vcc, s88, v240
	s_nop 1
	v_addc_co_u32_e32 v245, vcc, 0, v241, vcc
	global_load_dwordx4 v[240:243], v[242:243], off offset:640
	s_nop 0
	global_load_dwordx4 v[244:247], v[244:245], off offset:640
	ds_read_b128 v[102:105], v100 offset:8192
	ds_read_b128 v[106:109], v100
	ds_read_b128 v[110:113], v100 offset:10240
	s_waitcnt lgkmcnt(1)
	v_mfma_f32_16x16x32_bf16 v[76:79], v[102:105], v[106:109], v[76:79]
	s_waitcnt lgkmcnt(0)
	v_mfma_f32_16x16x32_bf16 v[72:75], v[110:113], v[106:109], v[72:75]
	ds_read_b128 v[106:109], v100 offset:2048
	s_waitcnt lgkmcnt(0)
	v_mfma_f32_16x16x32_bf16 v[60:63], v[102:105], v[106:109], v[60:63]
	v_mfma_f32_16x16x32_bf16 v[56:59], v[110:113], v[106:109], v[56:59]
	ds_read_b128 v[106:109], v100 offset:4096
	s_waitcnt lgkmcnt(0)
	v_mfma_f32_16x16x32_bf16 v[52:55], v[102:105], v[106:109], v[52:55]
	v_mfma_f32_16x16x32_bf16 v[44:47], v[110:113], v[106:109], v[44:47]
	ds_read_b128 v[106:109], v100 offset:6144
	s_waitcnt lgkmcnt(0)
	v_mfma_f32_16x16x32_bf16 v[36:39], v[102:105], v[106:109], v[36:39]
	ds_read_b128 v[102:105], v101 offset:8192
	v_mfma_f32_16x16x32_bf16 v[16:19], v[110:113], v[106:109], v[16:19]
	ds_read_b128 v[110:113], v101 offset:10240
	ds_read_b128 v[106:109], v101
	s_waitcnt lgkmcnt(0)
	v_mfma_f32_16x16x32_bf16 v[76:79], v[102:105], v[106:109], v[76:79]
	v_mfma_f32_16x16x32_bf16 v[72:75], v[110:113], v[106:109], v[72:75]
	ds_read_b128 v[106:109], v101 offset:2048
	s_waitcnt lgkmcnt(0)
	v_mfma_f32_16x16x32_bf16 v[60:63], v[102:105], v[106:109], v[60:63]
	v_mfma_f32_16x16x32_bf16 v[56:59], v[110:113], v[106:109], v[56:59]
	ds_read_b128 v[106:109], v101 offset:4096
	s_waitcnt lgkmcnt(0)
	v_mfma_f32_16x16x32_bf16 v[52:55], v[102:105], v[106:109], v[52:55]
	v_mfma_f32_16x16x32_bf16 v[44:47], v[110:113], v[106:109], v[44:47]
	ds_read_b128 v[106:109], v101 offset:6144
	s_waitcnt lgkmcnt(0)
	v_mfma_f32_16x16x32_bf16 v[36:39], v[102:105], v[106:109], v[36:39]
	v_mfma_f32_16x16x32_bf16 v[16:19], v[110:113], v[106:109], v[16:19]
	s_waitcnt vmcnt(35)
	ds_write_b128 v99, v[0:3]
	s_waitcnt vmcnt(34)
	ds_write_b128 v99, v[4:7] offset:1024
	s_waitcnt vmcnt(33)
	ds_write_b128 v99, v[8:11] offset:2048
	s_waitcnt vmcnt(32)
	ds_write_b128 v99, v[12:15] offset:3072
	s_waitcnt vmcnt(31)
	ds_write_b128 v99, v[20:23] offset:4096
	s_waitcnt vmcnt(30)
	ds_write_b128 v99, v[24:27] offset:5120
	s_waitcnt vmcnt(29)
	ds_write_b128 v99, v[28:31] offset:6144
	s_waitcnt vmcnt(28)
	ds_write_b128 v99, v[32:35] offset:7168
	s_waitcnt vmcnt(27)
	ds_write_b128 v99, v[40:43] offset:8192
	s_waitcnt vmcnt(26)
	ds_write_b128 v99, v[48:51] offset:9216
	s_waitcnt vmcnt(25)
	ds_write_b128 v99, v[64:67] offset:10240
	s_waitcnt vmcnt(24)
	ds_write_b128 v99, v[68:71] offset:11264
	v_lshl_add_u64 v[28:29], v[88:89], 0, s[36:37]
	v_add_co_u32_e32 v0, vcc, s45, v28
	v_lshl_add_u64 v[64:65], v[90:91], 0, s[36:37]
	s_nop 0
	v_addc_co_u32_e32 v1, vcc, 0, v29, vcc
	v_add_co_u32_e32 v4, vcc, s52, v28
	s_nop 1
	v_addc_co_u32_e32 v5, vcc, 0, v29, vcc
	v_add_co_u32_e32 v8, vcc, s53, v28
	global_load_dwordx4 v[0:3], v[0:1], off offset:768
	s_nop 0
	global_load_dwordx4 v[4:7], v[4:5], off offset:768
	v_addc_co_u32_e32 v9, vcc, 0, v29, vcc
	v_add_co_u32_e32 v12, vcc, s54, v28
	s_nop 1
	v_addc_co_u32_e32 v13, vcc, 0, v29, vcc
	v_add_co_u32_e32 v20, vcc, s56, v28
	global_load_dwordx4 v[8:11], v[8:9], off offset:768
	s_nop 0
	global_load_dwordx4 v[12:15], v[12:13], off offset:768
	v_addc_co_u32_e32 v21, vcc, 0, v29, vcc
	v_add_co_u32_e32 v24, vcc, s41, v28
	s_nop 1
	v_addc_co_u32_e32 v25, vcc, 0, v29, vcc
	v_add_co_u32_e32 v30, vcc, s42, v28
	global_load_dwordx4 v[20:23], v[20:21], off offset:768
	s_nop 0
	global_load_dwordx4 v[24:27], v[24:25], off offset:768
	v_addc_co_u32_e32 v31, vcc, 0, v29, vcc
	v_add_co_u32_e32 v32, vcc, s43, v28
	s_nop 1
	v_addc_co_u32_e32 v33, vcc, 0, v29, vcc
	v_add_co_u32_e32 v40, vcc, s44, v64
	global_load_dwordx4 v[28:31], v[30:31], off offset:768
	s_nop 0
	global_load_dwordx4 v[32:35], v[32:33], off offset:768
	v_addc_co_u32_e32 v41, vcc, 0, v65, vcc
	v_add_co_u32_e32 v48, vcc, s57, v64
	s_nop 1
	v_addc_co_u32_e32 v49, vcc, 0, v65, vcc
	v_add_co_u32_e32 v66, vcc, s75, v64
	global_load_dwordx4 v[40:43], v[40:41], off offset:768
	s_nop 0
	global_load_dwordx4 v[48:51], v[48:49], off offset:768
	v_addc_co_u32_e32 v67, vcc, 0, v65, vcc
	v_add_co_u32_e32 v68, vcc, s88, v64
	s_nop 1
	v_addc_co_u32_e32 v69, vcc, 0, v65, vcc
	global_load_dwordx4 v[64:67], v[66:67], off offset:768
	s_nop 0
	global_load_dwordx4 v[68:71], v[68:69], off offset:768
	ds_read_b128 v[102:105], v100 offset:8192
	ds_read_b128 v[106:109], v100
	ds_read_b128 v[110:113], v100 offset:10240
	s_waitcnt lgkmcnt(1)
	v_mfma_f32_16x16x32_bf16 v[76:79], v[102:105], v[106:109], v[76:79]
	s_waitcnt lgkmcnt(0)
	v_mfma_f32_16x16x32_bf16 v[72:75], v[110:113], v[106:109], v[72:75]
	ds_read_b128 v[106:109], v100 offset:2048
	s_waitcnt lgkmcnt(0)
	v_mfma_f32_16x16x32_bf16 v[60:63], v[102:105], v[106:109], v[60:63]
	v_mfma_f32_16x16x32_bf16 v[56:59], v[110:113], v[106:109], v[56:59]
	ds_read_b128 v[106:109], v100 offset:4096
	s_waitcnt lgkmcnt(0)
	v_mfma_f32_16x16x32_bf16 v[52:55], v[102:105], v[106:109], v[52:55]
	v_mfma_f32_16x16x32_bf16 v[44:47], v[110:113], v[106:109], v[44:47]
	ds_read_b128 v[106:109], v100 offset:6144
	s_waitcnt lgkmcnt(0)
	v_mfma_f32_16x16x32_bf16 v[36:39], v[102:105], v[106:109], v[36:39]
	ds_read_b128 v[102:105], v101 offset:8192
	v_mfma_f32_16x16x32_bf16 v[16:19], v[110:113], v[106:109], v[16:19]
	ds_read_b128 v[110:113], v101 offset:10240
	ds_read_b128 v[106:109], v101
	s_waitcnt lgkmcnt(0)
	v_mfma_f32_16x16x32_bf16 v[76:79], v[102:105], v[106:109], v[76:79]
	v_mfma_f32_16x16x32_bf16 v[72:75], v[110:113], v[106:109], v[72:75]
	ds_read_b128 v[106:109], v101 offset:2048
	s_waitcnt lgkmcnt(0)
	v_mfma_f32_16x16x32_bf16 v[60:63], v[102:105], v[106:109], v[60:63]
	v_mfma_f32_16x16x32_bf16 v[56:59], v[110:113], v[106:109], v[56:59]
	ds_read_b128 v[106:109], v101 offset:4096
	s_waitcnt lgkmcnt(0)
	v_mfma_f32_16x16x32_bf16 v[52:55], v[102:105], v[106:109], v[52:55]
	v_mfma_f32_16x16x32_bf16 v[44:47], v[110:113], v[106:109], v[44:47]
	ds_read_b128 v[106:109], v101 offset:6144
	s_waitcnt lgkmcnt(0)
	v_mfma_f32_16x16x32_bf16 v[36:39], v[102:105], v[106:109], v[36:39]
	v_mfma_f32_16x16x32_bf16 v[16:19], v[110:113], v[106:109], v[16:19]
	s_waitcnt vmcnt(35)
	ds_write_b128 v99, v[124:127]
	s_waitcnt vmcnt(34)
	ds_write_b128 v99, v[128:131] offset:1024
	s_waitcnt vmcnt(33)
	ds_write_b128 v99, v[132:135] offset:2048
	s_waitcnt vmcnt(32)
	ds_write_b128 v99, v[136:139] offset:3072
	s_waitcnt vmcnt(31)
	ds_write_b128 v99, v[140:143] offset:4096
	s_waitcnt vmcnt(30)
	ds_write_b128 v99, v[144:147] offset:5120
	s_waitcnt vmcnt(29)
	ds_write_b128 v99, v[148:151] offset:6144
	s_waitcnt vmcnt(28)
	ds_write_b128 v99, v[152:155] offset:7168
	s_waitcnt vmcnt(27)
	ds_write_b128 v99, v[156:159] offset:8192
	s_waitcnt vmcnt(26)
	ds_write_b128 v99, v[160:163] offset:9216
	s_waitcnt vmcnt(25)
	ds_write_b128 v99, v[164:167] offset:10240
	s_waitcnt vmcnt(24)
	ds_write_b128 v99, v[168:171] offset:11264
	v_lshl_add_u64 v[148:149], v[88:89], 0, s[36:37]
	v_add_co_u32_e32 v124, vcc, s45, v148
	v_lshl_add_u64 v[164:165], v[90:91], 0, s[36:37]
	s_nop 0
	v_addc_co_u32_e32 v125, vcc, 0, v149, vcc
	v_add_co_u32_e32 v128, vcc, s52, v148
	s_nop 1
	v_addc_co_u32_e32 v129, vcc, 0, v149, vcc
	v_add_co_u32_e32 v132, vcc, s53, v148
	global_load_dwordx4 v[124:127], v[124:125], off offset:896
	s_nop 0
	global_load_dwordx4 v[128:131], v[128:129], off offset:896
	v_addc_co_u32_e32 v133, vcc, 0, v149, vcc
	v_add_co_u32_e32 v136, vcc, s54, v148
	s_nop 1
	v_addc_co_u32_e32 v137, vcc, 0, v149, vcc
	v_add_co_u32_e32 v140, vcc, s56, v148
	global_load_dwordx4 v[132:135], v[132:133], off offset:896
	s_nop 0
	global_load_dwordx4 v[136:139], v[136:137], off offset:896
	v_addc_co_u32_e32 v141, vcc, 0, v149, vcc
	v_add_co_u32_e32 v144, vcc, s41, v148
	s_nop 1
	v_addc_co_u32_e32 v145, vcc, 0, v149, vcc
	v_add_co_u32_e32 v150, vcc, s42, v148
	global_load_dwordx4 v[140:143], v[140:141], off offset:896
	s_nop 0
	global_load_dwordx4 v[144:147], v[144:145], off offset:896
	v_addc_co_u32_e32 v151, vcc, 0, v149, vcc
	v_add_co_u32_e32 v152, vcc, s43, v148
	s_nop 1
	v_addc_co_u32_e32 v153, vcc, 0, v149, vcc
	v_add_co_u32_e32 v156, vcc, s44, v164
	global_load_dwordx4 v[148:151], v[150:151], off offset:896
	s_nop 0
	global_load_dwordx4 v[152:155], v[152:153], off offset:896
	v_addc_co_u32_e32 v157, vcc, 0, v165, vcc
	v_add_co_u32_e32 v160, vcc, s57, v164
	s_nop 1
	v_addc_co_u32_e32 v161, vcc, 0, v165, vcc
	v_add_co_u32_e32 v166, vcc, s75, v164
	global_load_dwordx4 v[156:159], v[156:157], off offset:896
	s_nop 0
	global_load_dwordx4 v[160:163], v[160:161], off offset:896
	v_addc_co_u32_e32 v167, vcc, 0, v165, vcc
	v_add_co_u32_e32 v168, vcc, s88, v164
	s_nop 1
	v_addc_co_u32_e32 v169, vcc, 0, v165, vcc
	global_load_dwordx4 v[164:167], v[166:167], off offset:896
	s_nop 0
	global_load_dwordx4 v[168:171], v[168:169], off offset:896
	ds_read_b128 v[102:105], v100 offset:8192
	ds_read_b128 v[106:109], v100
	ds_read_b128 v[110:113], v100 offset:10240
	s_waitcnt lgkmcnt(1)
	v_mfma_f32_16x16x32_bf16 v[76:79], v[102:105], v[106:109], v[76:79]
	s_waitcnt lgkmcnt(0)
	v_mfma_f32_16x16x32_bf16 v[72:75], v[110:113], v[106:109], v[72:75]
	ds_read_b128 v[106:109], v100 offset:2048
	s_waitcnt lgkmcnt(0)
	v_mfma_f32_16x16x32_bf16 v[60:63], v[102:105], v[106:109], v[60:63]
	v_mfma_f32_16x16x32_bf16 v[56:59], v[110:113], v[106:109], v[56:59]
	ds_read_b128 v[106:109], v100 offset:4096
	s_waitcnt lgkmcnt(0)
	v_mfma_f32_16x16x32_bf16 v[52:55], v[102:105], v[106:109], v[52:55]
	v_mfma_f32_16x16x32_bf16 v[44:47], v[110:113], v[106:109], v[44:47]
	ds_read_b128 v[106:109], v100 offset:6144
	s_waitcnt lgkmcnt(0)
	v_mfma_f32_16x16x32_bf16 v[36:39], v[102:105], v[106:109], v[36:39]
	ds_read_b128 v[102:105], v101 offset:8192
	v_mfma_f32_16x16x32_bf16 v[16:19], v[110:113], v[106:109], v[16:19]
	ds_read_b128 v[110:113], v101 offset:10240
	ds_read_b128 v[106:109], v101
	s_waitcnt lgkmcnt(0)
	v_mfma_f32_16x16x32_bf16 v[76:79], v[102:105], v[106:109], v[76:79]
	v_mfma_f32_16x16x32_bf16 v[72:75], v[110:113], v[106:109], v[72:75]
	ds_read_b128 v[106:109], v101 offset:2048
	s_waitcnt lgkmcnt(0)
	v_mfma_f32_16x16x32_bf16 v[60:63], v[102:105], v[106:109], v[60:63]
	v_mfma_f32_16x16x32_bf16 v[56:59], v[110:113], v[106:109], v[56:59]
	ds_read_b128 v[106:109], v101 offset:4096
	s_waitcnt lgkmcnt(0)
	v_mfma_f32_16x16x32_bf16 v[52:55], v[102:105], v[106:109], v[52:55]
	v_mfma_f32_16x16x32_bf16 v[44:47], v[110:113], v[106:109], v[44:47]
	ds_read_b128 v[106:109], v101 offset:6144
	s_waitcnt lgkmcnt(0)
	v_mfma_f32_16x16x32_bf16 v[36:39], v[102:105], v[106:109], v[36:39]
	v_mfma_f32_16x16x32_bf16 v[16:19], v[110:113], v[106:109], v[16:19]
	s_waitcnt vmcnt(35)
	ds_write_b128 v99, v[172:175]
	s_waitcnt vmcnt(34)
	ds_write_b128 v99, v[176:179] offset:1024
	s_waitcnt vmcnt(33)
	ds_write_b128 v99, v[180:183] offset:2048
	s_waitcnt vmcnt(32)
	ds_write_b128 v99, v[184:187] offset:3072
	s_waitcnt vmcnt(31)
	ds_write_b128 v99, v[188:191] offset:4096
	s_waitcnt vmcnt(30)
	ds_write_b128 v99, v[192:195] offset:5120
	s_waitcnt vmcnt(29)
	ds_write_b128 v99, v[196:199] offset:6144
	s_waitcnt vmcnt(28)
	ds_write_b128 v99, v[200:203] offset:7168
	s_waitcnt vmcnt(27)
	ds_write_b128 v99, v[204:207] offset:8192
	s_waitcnt vmcnt(26)
	ds_write_b128 v99, v[216:219] offset:9216
	s_waitcnt vmcnt(25)
	ds_write_b128 v99, v[240:243] offset:10240
	s_waitcnt vmcnt(24)
	ds_write_b128 v99, v[244:247] offset:11264
	ds_read_b128 v[102:105], v100 offset:8192
	ds_read_b128 v[106:109], v100
	ds_read_b128 v[110:113], v100 offset:10240
	s_waitcnt lgkmcnt(1)
	v_mfma_f32_16x16x32_bf16 v[76:79], v[102:105], v[106:109], v[76:79]
	s_waitcnt lgkmcnt(0)
	v_mfma_f32_16x16x32_bf16 v[72:75], v[110:113], v[106:109], v[72:75]
	ds_read_b128 v[106:109], v100 offset:2048
	s_waitcnt lgkmcnt(0)
	v_mfma_f32_16x16x32_bf16 v[60:63], v[102:105], v[106:109], v[60:63]
	v_mfma_f32_16x16x32_bf16 v[56:59], v[110:113], v[106:109], v[56:59]
	ds_read_b128 v[106:109], v100 offset:4096
	s_waitcnt lgkmcnt(0)
	v_mfma_f32_16x16x32_bf16 v[52:55], v[102:105], v[106:109], v[52:55]
	v_mfma_f32_16x16x32_bf16 v[44:47], v[110:113], v[106:109], v[44:47]
	ds_read_b128 v[106:109], v100 offset:6144
	s_waitcnt lgkmcnt(0)
	v_mfma_f32_16x16x32_bf16 v[36:39], v[102:105], v[106:109], v[36:39]
	ds_read_b128 v[102:105], v101 offset:8192
	v_mfma_f32_16x16x32_bf16 v[16:19], v[110:113], v[106:109], v[16:19]
	ds_read_b128 v[110:113], v101 offset:10240
	ds_read_b128 v[106:109], v101
	s_waitcnt lgkmcnt(0)
	v_mfma_f32_16x16x32_bf16 v[76:79], v[102:105], v[106:109], v[76:79]
	v_mfma_f32_16x16x32_bf16 v[72:75], v[110:113], v[106:109], v[72:75]
	ds_read_b128 v[106:109], v101 offset:2048
	s_waitcnt lgkmcnt(0)
	v_mfma_f32_16x16x32_bf16 v[60:63], v[102:105], v[106:109], v[60:63]
	v_mfma_f32_16x16x32_bf16 v[56:59], v[110:113], v[106:109], v[56:59]
	ds_read_b128 v[106:109], v101 offset:4096
	s_waitcnt lgkmcnt(0)
	v_mfma_f32_16x16x32_bf16 v[52:55], v[102:105], v[106:109], v[52:55]
	v_mfma_f32_16x16x32_bf16 v[44:47], v[110:113], v[106:109], v[44:47]
	ds_read_b128 v[106:109], v101 offset:6144
	s_waitcnt lgkmcnt(0)
	v_mfma_f32_16x16x32_bf16 v[36:39], v[102:105], v[106:109], v[36:39]
	v_mfma_f32_16x16x32_bf16 v[16:19], v[110:113], v[106:109], v[16:19]
	s_waitcnt vmcnt(23)
	ds_write_b128 v99, v[0:3]
	s_waitcnt vmcnt(22)
	ds_write_b128 v99, v[4:7] offset:1024
	s_waitcnt vmcnt(21)
	ds_write_b128 v99, v[8:11] offset:2048
	s_waitcnt vmcnt(20)
	ds_write_b128 v99, v[12:15] offset:3072
	s_waitcnt vmcnt(19)
	ds_write_b128 v99, v[20:23] offset:4096
	s_waitcnt vmcnt(18)
	ds_write_b128 v99, v[24:27] offset:5120
	s_waitcnt vmcnt(17)
	ds_write_b128 v99, v[28:31] offset:6144
	s_waitcnt vmcnt(16)
	ds_write_b128 v99, v[32:35] offset:7168
	s_waitcnt vmcnt(15)
	ds_write_b128 v99, v[40:43] offset:8192
	s_waitcnt vmcnt(14)
	ds_write_b128 v99, v[48:51] offset:9216
	s_waitcnt vmcnt(13)
	ds_write_b128 v99, v[64:67] offset:10240
	s_waitcnt vmcnt(12)
	ds_write_b128 v99, v[68:71] offset:11264
	ds_read_b128 v[102:105], v100 offset:8192
	ds_read_b128 v[106:109], v100
	ds_read_b128 v[110:113], v100 offset:10240
	s_waitcnt lgkmcnt(1)
	v_mfma_f32_16x16x32_bf16 v[76:79], v[102:105], v[106:109], v[76:79]
	s_waitcnt lgkmcnt(0)
	v_mfma_f32_16x16x32_bf16 v[72:75], v[110:113], v[106:109], v[72:75]
	ds_read_b128 v[106:109], v100 offset:2048
	s_waitcnt lgkmcnt(0)
	v_mfma_f32_16x16x32_bf16 v[60:63], v[102:105], v[106:109], v[60:63]
	v_mfma_f32_16x16x32_bf16 v[56:59], v[110:113], v[106:109], v[56:59]
	ds_read_b128 v[106:109], v100 offset:4096
	s_waitcnt lgkmcnt(0)
	v_mfma_f32_16x16x32_bf16 v[52:55], v[102:105], v[106:109], v[52:55]
	v_mfma_f32_16x16x32_bf16 v[44:47], v[110:113], v[106:109], v[44:47]
	ds_read_b128 v[106:109], v100 offset:6144
	s_waitcnt lgkmcnt(0)
	v_mfma_f32_16x16x32_bf16 v[36:39], v[102:105], v[106:109], v[36:39]
	ds_read_b128 v[102:105], v101 offset:8192
	v_mfma_f32_16x16x32_bf16 v[16:19], v[110:113], v[106:109], v[16:19]
	ds_read_b128 v[110:113], v101 offset:10240
	ds_read_b128 v[106:109], v101
	s_waitcnt lgkmcnt(0)
	v_mfma_f32_16x16x32_bf16 v[76:79], v[102:105], v[106:109], v[76:79]
	v_mfma_f32_16x16x32_bf16 v[72:75], v[110:113], v[106:109], v[72:75]
	ds_read_b128 v[106:109], v101 offset:2048
	s_waitcnt lgkmcnt(0)
	v_mfma_f32_16x16x32_bf16 v[60:63], v[102:105], v[106:109], v[60:63]
	v_mfma_f32_16x16x32_bf16 v[56:59], v[110:113], v[106:109], v[56:59]
	ds_read_b128 v[106:109], v101 offset:4096
	s_waitcnt lgkmcnt(0)
	v_mfma_f32_16x16x32_bf16 v[52:55], v[102:105], v[106:109], v[52:55]
	v_mfma_f32_16x16x32_bf16 v[44:47], v[110:113], v[106:109], v[44:47]
	ds_read_b128 v[106:109], v101 offset:6144
	s_waitcnt lgkmcnt(0)
	v_mfma_f32_16x16x32_bf16 v[36:39], v[102:105], v[106:109], v[36:39]
	v_mfma_f32_16x16x32_bf16 v[16:19], v[110:113], v[106:109], v[16:19]
	s_waitcnt vmcnt(11)
	ds_write_b128 v99, v[124:127]
	s_waitcnt vmcnt(10)
	ds_write_b128 v99, v[128:131] offset:1024
	s_waitcnt vmcnt(9)
	ds_write_b128 v99, v[132:135] offset:2048
	s_waitcnt vmcnt(8)
	ds_write_b128 v99, v[136:139] offset:3072
	s_waitcnt vmcnt(7)
	ds_write_b128 v99, v[140:143] offset:4096
	s_waitcnt vmcnt(6)
	ds_write_b128 v99, v[144:147] offset:5120
	s_waitcnt vmcnt(5)
	ds_write_b128 v99, v[148:151] offset:6144
	s_waitcnt vmcnt(4)
	ds_write_b128 v99, v[152:155] offset:7168
	s_waitcnt vmcnt(3)
	ds_write_b128 v99, v[156:159] offset:8192
	s_waitcnt vmcnt(2)
	ds_write_b128 v99, v[160:163] offset:9216
	s_waitcnt vmcnt(1)
	ds_write_b128 v99, v[164:167] offset:10240
	s_waitcnt vmcnt(0)
	ds_write_b128 v99, v[168:171] offset:11264
	ds_read_b128 v[0:3], v100 offset:8192
	ds_read_b128 v[4:7], v100
	ds_read_b128 v[12:15], v100 offset:10240
	ds_read_b128 v[40:43], v100 offset:6144
	ds_read_b128 v[20:23], v100 offset:2048
	ds_read_b128 v[28:31], v100 offset:4096
	s_waitcnt lgkmcnt(4)
	v_mfma_f32_16x16x32_bf16 v[8:11], v[0:3], v[4:7], v[76:79]
	s_waitcnt lgkmcnt(3)
	v_mfma_f32_16x16x32_bf16 v[4:7], v[12:15], v[4:7], v[72:75]
	s_waitcnt lgkmcnt(1)
	v_mfma_f32_16x16x32_bf16 v[24:27], v[0:3], v[20:23], v[60:63]
	v_mfma_f32_16x16x32_bf16 v[20:23], v[12:15], v[20:23], v[56:59]
	s_waitcnt lgkmcnt(0)
	v_mfma_f32_16x16x32_bf16 v[32:35], v[0:3], v[28:31], v[52:55]
	v_mfma_f32_16x16x32_bf16 v[28:31], v[12:15], v[28:31], v[44:47]
	v_mfma_f32_16x16x32_bf16 v[0:3], v[0:3], v[40:43], v[36:39]
	s_nop 2
	ds_read_b128 v[36:39], v101 offset:8192
	v_mfma_f32_16x16x32_bf16 v[12:15], v[12:15], v[40:43], v[16:19]
	ds_read_b128 v[40:43], v101 offset:10240
	s_nop 1
	ds_read_b128 v[16:19], v101
	s_waitcnt lgkmcnt(0)
	v_mfma_f32_16x16x32_bf16 v[8:11], v[36:39], v[16:19], v[8:11]
	v_mfma_f32_16x16x32_bf16 v[4:7], v[40:43], v[16:19], v[4:7]
	ds_read_b128 v[16:19], v101 offset:2048
	s_waitcnt lgkmcnt(0)
	v_mfma_f32_16x16x32_bf16 v[24:27], v[36:39], v[16:19], v[24:27]
	v_mfma_f32_16x16x32_bf16 v[16:19], v[40:43], v[16:19], v[20:23]
	s_nop 2
	ds_read_b128 v[20:23], v101 offset:4096
	s_waitcnt lgkmcnt(0)
	v_mfma_f32_16x16x32_bf16 v[32:35], v[36:39], v[20:23], v[32:35]
	v_mfma_f32_16x16x32_bf16 v[20:23], v[40:43], v[20:23], v[28:31]
	s_nop 2
	ds_read_b128 v[28:31], v101 offset:6144
	s_waitcnt lgkmcnt(0)
	v_mfma_f32_16x16x32_bf16 v[0:3], v[36:39], v[28:31], v[0:3]
	v_mfma_f32_16x16x32_bf16 v[12:15], v[40:43], v[28:31], v[12:15]
	s_barrier
	ds_write_b128 v94, v[8:11]
	ds_write_b128 v94, v[4:7] offset:1024
	ds_write_b128 v94, v[24:27] offset:2048
	ds_write_b128 v94, v[16:19] offset:3072
	ds_write_b128 v94, v[32:35] offset:4096
	ds_write_b128 v94, v[20:23] offset:5120
	ds_write_b128 v94, v[0:3] offset:6144
	ds_write_b128 v94, v[12:15] offset:7168
	s_waitcnt lgkmcnt(0)
	s_barrier
	s_and_saveexec_b64 s[36:37], s[2:3]
	s_cbranch_execz .LBB0_1004
	ds_read_b128 v[0:3], v95
	ds_read_b128 v[4:7], v95 offset:8192
	v_add_u32_e32 v10, s40, v98
	v_ashrrev_i32_e32 v11, 31, v10
	v_lshlrev_b64 v[12:13], 2, v[10:11]
	s_waitcnt lgkmcnt(0)
	v_pk_add_f32 v[6:7], v[2:3], v[6:7]
	v_pk_add_f32 v[4:5], v[0:1], v[4:5]
	ds_read_b128 v[0:3], v95 offset:16384
	s_waitcnt lgkmcnt(0)
	v_pk_add_f32 v[6:7], v[6:7], v[2:3]
	v_pk_add_f32 v[4:5], v[4:5], v[0:1]
	ds_read_b128 v[0:3], v95 offset:24576
	s_waitcnt lgkmcnt(0)
	v_pk_add_f32 v[6:7], v[6:7], v[2:3]
	v_pk_add_f32 v[4:5], v[4:5], v[0:1]
	ds_read_b128 v[0:3], v95 offset:32768
	s_waitcnt lgkmcnt(0)
	v_pk_add_f32 v[6:7], v[6:7], v[2:3]
	v_pk_add_f32 v[4:5], v[4:5], v[0:1]
	ds_read_b128 v[0:3], v95 offset:40960
	s_waitcnt lgkmcnt(0)
	v_pk_add_f32 v[6:7], v[6:7], v[2:3]
	v_pk_add_f32 v[4:5], v[4:5], v[0:1]
	ds_read_b128 v[0:3], v95 offset:49152
	s_waitcnt lgkmcnt(0)
	v_pk_add_f32 v[6:7], v[6:7], v[2:3]
	v_pk_add_f32 v[4:5], v[4:5], v[0:1]
	ds_read_b128 v[0:3], v95 offset:57344
	s_waitcnt lgkmcnt(0)
	v_pk_add_f32 v[8:9], v[4:5], v[0:1]
	v_add_u32_e32 v0, s39, v96
	v_or_b32_e32 v4, v0, v97
	v_add_u32_e32 v1, 0xffffc000, v4
	v_lshrrev_b32_e32 v1, 2, v1
	v_cmp_gt_i32_e32 vcc, s74, v4
	v_ashrrev_i32_e32 v0, 12, v0
	v_add_u32_e32 v1, 4, v1
	v_ashrrev_i32_e32 v5, 31, v4
	v_pk_add_f32 v[6:7], v[6:7], v[2:3]
	v_cndmask_b32_e32 v2, v1, v0, vcc
	v_mov_b64_e32 v[0:1], s[30:31]
	v_lshlrev_b64 v[14:15], 11, v[4:5]
	v_mad_i64_i32 v[0:1], s[40:41], v2, s33, v[0:1]
	v_lshl_add_u64 v[14:15], s[34:35], 0, v[14:15]
	v_lshl_add_u64 v[0:1], v[0:1], 0, v[12:13]
	v_lshl_add_u64 v[10:11], v[10:11], 1, v[14:15]
	global_load_dwordx4 v[0:3], v[0:1], off
	s_andn2_b64 vcc, exec, s[22:23]
	global_load_dwordx2 v[10:11], v[10:11], off
	s_waitcnt vmcnt(0)
	v_lshlrev_b32_e32 v14, 16, v10
	v_and_b32_e32 v15, 0xffff0000, v10
	v_lshlrev_b32_e32 v10, 16, v11
	v_and_b32_e32 v11, 0xffff0000, v11
	v_pk_fma_f32 v[2:3], v[6:7], v[2:3], v[10:11]
	v_lshlrev_b64 v[6:7], 12, v[4:5]
	v_lshl_add_u64 v[6:7], s[6:7], 0, v[6:7]
	v_pk_fma_f32 v[0:1], v[8:9], v[0:1], v[14:15]
	v_lshl_add_u64 v[6:7], v[6:7], 0, v[12:13]
	global_store_dwordx4 v[6:7], v[0:3], off
	s_cbranch_vccnz .LBB0_1004
	s_nop 0
	v_mul_f32_e32 v1, v1, v1
	v_fmac_f32_e32 v1, v0, v0
	v_mul_f32_e32 v0, v3, v3
	v_fmac_f32_e32 v0, v2, v2
	v_add_f32_e32 v0, v1, v0
	ds_bpermute_b32 v1, v233, v0
	s_waitcnt lgkmcnt(0)
	v_add_f32_e32 v0, v0, v1
	ds_bpermute_b32 v1, v234, v0
	s_and_b64 exec, exec, s[4:5]
	s_cbranch_execz .LBB0_1004
	s_waitcnt lgkmcnt(0)
	v_add_f32_e32 v2, v0, v1
	v_lshl_add_u64 v[0:1], v[4:5], 2, s[28:29]
	global_atomic_add_f32 v[0:1], v2, off
	s_branch .LBB0_1004

.LBB0_1175:
	v_readlane_b32 s2, v250, 49
	v_mov_b32_e32 v0, s80
	v_readlane_b32 s3, v250, 50
	ds_read_b32 v0, v0 offset:8
	s_nop 3
	s_add_u32 s2, s2, 0x1000
	s_addc_u32 s3, s3, 0
	s_nop 1
	global_load_dword v1, v209, s[2:3] sc1
	s_waitcnt vmcnt(0) lgkmcnt(0)
	v_cmp_ne_u32_e32 vcc, v1, v0
	s_cbranch_vccz .LBB0_1176
	s_getpc_b64 s[98:99]

.LBB0_1180:
	v_readlane_b32 s2, v250, 49
	v_readlane_b32 s3, v250, 50
	s_add_i32 s8, s8, 1
	s_mov_b64 s[4:5], -1
	s_nop 2
	s_add_u32 s2, s2, 0x1000
	s_addc_u32 s3, s3, 0
	s_nop 1
	global_load_dword v1, v209, s[2:3] sc1
	s_waitcnt vmcnt(0)
	v_cmp_ne_u32_e64 s[2:3], v1, v0
	s_branch .LBB0_1177
